# v071 without the relaxed first-iteration vmcnt waits (plain vmcnt(8) as in the baseline; fewer VALU/branches in the GEMM load segments)
# speedup vs baseline: 1.0050x; 1.0050x over previous
.LBB0_352:
	s_add_u32 s44, s42, 0xfff80080
	s_addc_u32 s45, s43, -1
	s_add_i32 s55, 0, 0x10000
	s_cmp_eq_u32 s54, 28
	s_cselect_b32 s53, s17, s45
	s_cselect_b32 s52, s18, s44
	v_add_u32_e32 v150, s55, v158
	s_cselect_b32 s45, s5, s33
	s_cselect_b32 s44, s20, s28
	s_add_i32 s61, 0, 0x14000
	ds_read_b128 v[130:133], v150
	ds_read_b128 v[160:163], v150 offset:1024
	ds_read_b128 v[164:167], v150 offset:2048
	ds_read_b128 v[168:171], v150 offset:3072
	v_add_u32_e32 v150, s61, v158
	ds_read_b128 v[172:175], v150
	ds_read_b128 v[176:179], v150 offset:1024
	ds_read_b128 v[180:183], v150 offset:2048
	ds_read_b128 v[184:187], v150 offset:3072
	s_add_i32 m0, s35, 0xc000
	ds_read_b128 v[188:191], v159
	ds_read_b128 v[192:195], v159 offset:1024
	ds_read_b128 v[196:199], v159 offset:2048
	ds_read_b128 v[210:213], v159 offset:3072
	ds_read_b128 v[214:217], v159 offset:4096
	ds_read_b128 v[218:221], v159 offset:5120
	ds_read_b128 v[222:225], v159 offset:6144
	ds_read_b128 v[226:229], v159 offset:7168
	global_load_lds_dwordx4 v146, s[42:43]
	s_add_i32 m0, s35, 0xe000
	s_nop 0
	global_load_lds_dwordx4 v148, s[42:43]
	s_waitcnt vmcnt(8)
	s_waitcnt lgkmcnt(0)
	s_setprio 1
	s_barrier
	v_mfma_f32_16x16x32_bf16 v[126:129], v[130:133], v[188:191], v[126:129]
	v_mfma_f32_16x16x32_bf16 v[122:125], v[164:167], v[188:191], v[122:125]
	v_mfma_f32_16x16x32_bf16 v[110:113], v[130:133], v[196:199], v[110:113]
	v_mfma_f32_16x16x32_bf16 v[106:109], v[164:167], v[196:199], v[106:109]
	v_mfma_f32_16x16x32_bf16 v[92:95], v[130:133], v[214:217], v[92:95]
	v_mfma_f32_16x16x32_bf16 v[88:91], v[164:167], v[214:217], v[88:91]
	v_mfma_f32_16x16x32_bf16 v[76:79], v[130:133], v[222:225], v[76:79]
	v_mfma_f32_16x16x32_bf16 v[72:75], v[164:167], v[222:225], v[72:75]
	v_mfma_f32_16x16x32_bf16 v[126:129], v[160:163], v[192:195], v[126:129]
	v_mfma_f32_16x16x32_bf16 v[122:125], v[168:171], v[192:195], v[122:125]
	v_mfma_f32_16x16x32_bf16 v[110:113], v[160:163], v[210:213], v[110:113]
	v_mfma_f32_16x16x32_bf16 v[106:109], v[168:171], v[210:213], v[106:109]
	v_mfma_f32_16x16x32_bf16 v[92:95], v[160:163], v[218:221], v[92:95]
	v_mfma_f32_16x16x32_bf16 v[88:91], v[168:171], v[218:221], v[88:91]
	v_mfma_f32_16x16x32_bf16 v[76:79], v[160:163], v[226:229], v[76:79]
	v_mfma_f32_16x16x32_bf16 v[72:75], v[168:171], v[226:229], v[72:75]
	v_mfma_f32_16x16x32_bf16 v[118:121], v[172:175], v[188:191], v[118:121]
	v_mfma_f32_16x16x32_bf16 v[114:117], v[180:183], v[188:191], v[114:117]
	v_mfma_f32_16x16x32_bf16 v[102:105], v[172:175], v[196:199], v[102:105]
	v_mfma_f32_16x16x32_bf16 v[98:101], v[180:183], v[196:199], v[98:101]
	v_mfma_f32_16x16x32_bf16 v[84:87], v[172:175], v[214:217], v[84:87]
	v_mfma_f32_16x16x32_bf16 v[80:83], v[180:183], v[214:217], v[80:83]
	v_mfma_f32_16x16x32_bf16 v[68:71], v[172:175], v[222:225], v[68:71]
	v_mfma_f32_16x16x32_bf16 v[64:67], v[180:183], v[222:225], v[64:67]
	v_mfma_f32_16x16x32_bf16 v[118:121], v[176:179], v[192:195], v[118:121]
	v_mfma_f32_16x16x32_bf16 v[114:117], v[184:187], v[192:195], v[114:117]
	v_mfma_f32_16x16x32_bf16 v[102:105], v[176:179], v[210:213], v[102:105]
	v_mfma_f32_16x16x32_bf16 v[98:101], v[184:187], v[210:213], v[98:101]
	v_mfma_f32_16x16x32_bf16 v[84:87], v[176:179], v[218:221], v[84:87]
	v_mfma_f32_16x16x32_bf16 v[80:83], v[184:187], v[218:221], v[80:83]
	v_mfma_f32_16x16x32_bf16 v[68:71], v[176:179], v[226:229], v[68:71]
	v_mfma_f32_16x16x32_bf16 v[64:67], v[184:187], v[226:229], v[64:67]
	s_barrier
	s_setprio 0
	s_add_i32 s55, s55, s75
	s_mov_b32 m0, s55
	ds_read_b128 v[188:191], v159 offset:16384
	ds_read_b128 v[192:195], v159 offset:17408
	ds_read_b128 v[196:199], v159 offset:18432
	ds_read_b128 v[210:213], v159 offset:19456
	ds_read_b128 v[214:217], v159 offset:20480
	ds_read_b128 v[218:221], v159 offset:21504
	ds_read_b128 v[222:225], v159 offset:22528
	ds_read_b128 v[226:229], v159 offset:23552
	global_load_lds_dwordx4 v142, s[44:45]
	s_add_i32 m0, s55, 0x2000
	s_add_u32 s56, s44, 0x80000
	s_addc_u32 s57, s45, 0
	s_add_i32 s55, s61, s75
	global_load_lds_dwordx4 v138, s[44:45]
	s_mov_b32 m0, s55
	s_nop 0
	global_load_lds_dwordx4 v142, s[56:57]
	s_add_i32 m0, s55, 0x2000
	s_nop 0
	global_load_lds_dwordx4 v138, s[56:57]
	s_mov_b32 m0, s35
	s_nop 0
	global_load_lds_dwordx4 v144, s[52:53]
	s_mov_b32 m0, s68
	s_nop 0
	global_load_lds_dwordx4 v140, s[52:53]
	s_waitcnt vmcnt(8)
	v_mov_b32_e32 v243, 0
	s_waitcnt lgkmcnt(0)
	s_setprio 1
	s_barrier
	v_mfma_f32_16x16x32_bf16 v[60:63], v[130:133], v[188:191], v[60:63]
	v_mfma_f32_16x16x32_bf16 v[56:59], v[164:167], v[188:191], v[56:59]
	v_mfma_f32_16x16x32_bf16 v[44:47], v[130:133], v[196:199], v[44:47]
	v_mfma_f32_16x16x32_bf16 v[40:43], v[164:167], v[196:199], v[40:43]
	v_mfma_f32_16x16x32_bf16 v[28:31], v[130:133], v[214:217], v[28:31]
	v_mfma_f32_16x16x32_bf16 v[24:27], v[164:167], v[214:217], v[24:27]
	v_mfma_f32_16x16x32_bf16 v[12:15], v[130:133], v[222:225], v[12:15]
	v_mfma_f32_16x16x32_bf16 v[8:11], v[164:167], v[222:225], v[8:11]
	v_mfma_f32_16x16x32_bf16 v[60:63], v[160:163], v[192:195], v[60:63]
	v_mfma_f32_16x16x32_bf16 v[56:59], v[168:171], v[192:195], v[56:59]
	v_mfma_f32_16x16x32_bf16 v[44:47], v[160:163], v[210:213], v[44:47]
	v_mfma_f32_16x16x32_bf16 v[40:43], v[168:171], v[210:213], v[40:43]
	v_mfma_f32_16x16x32_bf16 v[28:31], v[160:163], v[218:221], v[28:31]
	v_mfma_f32_16x16x32_bf16 v[24:27], v[168:171], v[218:221], v[24:27]
	v_mfma_f32_16x16x32_bf16 v[12:15], v[160:163], v[226:229], v[12:15]
	v_mfma_f32_16x16x32_bf16 v[8:11], v[168:171], v[226:229], v[8:11]
	v_mfma_f32_16x16x32_bf16 v[52:55], v[172:175], v[188:191], v[52:55]
	v_mfma_f32_16x16x32_bf16 v[48:51], v[180:183], v[188:191], v[48:51]
	v_mfma_f32_16x16x32_bf16 v[36:39], v[172:175], v[196:199], v[36:39]
	v_mfma_f32_16x16x32_bf16 v[32:35], v[180:183], v[196:199], v[32:35]
	v_mfma_f32_16x16x32_bf16 v[20:23], v[172:175], v[214:217], v[20:23]
	v_mfma_f32_16x16x32_bf16 v[16:19], v[180:183], v[214:217], v[16:19]
	v_mfma_f32_16x16x32_bf16 v[4:7], v[172:175], v[222:225], v[4:7]
	v_mfma_f32_16x16x32_bf16 v[0:3], v[180:183], v[222:225], v[0:3]
	v_mfma_f32_16x16x32_bf16 v[52:55], v[176:179], v[192:195], v[52:55]
	v_mfma_f32_16x16x32_bf16 v[48:51], v[184:187], v[192:195], v[48:51]
	v_mfma_f32_16x16x32_bf16 v[36:39], v[176:179], v[210:213], v[36:39]
	v_mfma_f32_16x16x32_bf16 v[32:35], v[184:187], v[210:213], v[32:35]
	v_mfma_f32_16x16x32_bf16 v[20:23], v[176:179], v[218:221], v[20:23]
	v_mfma_f32_16x16x32_bf16 v[16:19], v[184:187], v[218:221], v[16:19]
	v_mfma_f32_16x16x32_bf16 v[4:7], v[176:179], v[226:229], v[4:7]
	v_mfma_f32_16x16x32_bf16 v[0:3], v[184:187], v[226:229], v[0:3]
	s_barrier
	s_setprio 0
	s_add_i32 s55, 0, 0x18000
	s_add_i32 s56, 0, 0x1c000
	v_add_u32_e32 v168, s55, v158
	v_add_u32_e32 v184, s56, v158
	ds_read_b128 v[130:133], v168
	ds_read_b128 v[160:163], v168 offset:1024
	ds_read_b128 v[164:167], v168 offset:2048
	ds_read_b128 v[168:171], v168 offset:3072
	ds_read_b128 v[172:175], v184
	ds_read_b128 v[176:179], v184 offset:1024
	ds_read_b128 v[180:183], v184 offset:2048
	ds_read_b128 v[184:187], v184 offset:3072
	s_mov_b32 m0, s69
	ds_read_b128 v[188:191], v159 offset:32768
	ds_read_b128 v[192:195], v159 offset:33792
	ds_read_b128 v[196:199], v159 offset:34816
	ds_read_b128 v[210:213], v159 offset:35840
	ds_read_b128 v[214:217], v159 offset:36864
	ds_read_b128 v[218:221], v159 offset:37888
	ds_read_b128 v[222:225], v159 offset:38912
	ds_read_b128 v[226:229], v159 offset:39936
	global_load_lds_dwordx4 v202, s[52:53]
	s_mov_b32 m0, s77
	s_nop 0
	global_load_lds_dwordx4 v203, s[52:53]
	s_waitcnt vmcnt(8)
	s_waitcnt lgkmcnt(0)
	s_setprio 1
	s_barrier
	v_mfma_f32_16x16x32_bf16 v[126:129], v[130:133], v[188:191], v[126:129]
	v_mfma_f32_16x16x32_bf16 v[122:125], v[164:167], v[188:191], v[122:125]
	v_mfma_f32_16x16x32_bf16 v[110:113], v[130:133], v[196:199], v[110:113]
	v_mfma_f32_16x16x32_bf16 v[106:109], v[164:167], v[196:199], v[106:109]
	v_mfma_f32_16x16x32_bf16 v[92:95], v[130:133], v[214:217], v[92:95]
	v_mfma_f32_16x16x32_bf16 v[88:91], v[164:167], v[214:217], v[88:91]
	v_mfma_f32_16x16x32_bf16 v[76:79], v[130:133], v[222:225], v[76:79]
	v_mfma_f32_16x16x32_bf16 v[72:75], v[164:167], v[222:225], v[72:75]
	v_mfma_f32_16x16x32_bf16 v[126:129], v[160:163], v[192:195], v[126:129]
	v_mfma_f32_16x16x32_bf16 v[122:125], v[168:171], v[192:195], v[122:125]
	v_mfma_f32_16x16x32_bf16 v[110:113], v[160:163], v[210:213], v[110:113]
	v_mfma_f32_16x16x32_bf16 v[106:109], v[168:171], v[210:213], v[106:109]
	v_mfma_f32_16x16x32_bf16 v[92:95], v[160:163], v[218:221], v[92:95]
	v_mfma_f32_16x16x32_bf16 v[88:91], v[168:171], v[218:221], v[88:91]
	v_mfma_f32_16x16x32_bf16 v[76:79], v[160:163], v[226:229], v[76:79]
	v_mfma_f32_16x16x32_bf16 v[72:75], v[168:171], v[226:229], v[72:75]
	v_mfma_f32_16x16x32_bf16 v[118:121], v[172:175], v[188:191], v[118:121]
	v_mfma_f32_16x16x32_bf16 v[114:117], v[180:183], v[188:191], v[114:117]
	v_mfma_f32_16x16x32_bf16 v[102:105], v[172:175], v[196:199], v[102:105]
	v_mfma_f32_16x16x32_bf16 v[98:101], v[180:183], v[196:199], v[98:101]
	v_mfma_f32_16x16x32_bf16 v[84:87], v[172:175], v[214:217], v[84:87]
	v_mfma_f32_16x16x32_bf16 v[80:83], v[180:183], v[214:217], v[80:83]
	v_mfma_f32_16x16x32_bf16 v[68:71], v[172:175], v[222:225], v[68:71]
	v_mfma_f32_16x16x32_bf16 v[64:67], v[180:183], v[222:225], v[64:67]
	v_mfma_f32_16x16x32_bf16 v[118:121], v[176:179], v[192:195], v[118:121]
	v_mfma_f32_16x16x32_bf16 v[114:117], v[184:187], v[192:195], v[114:117]
	v_mfma_f32_16x16x32_bf16 v[102:105], v[176:179], v[210:213], v[102:105]
	v_mfma_f32_16x16x32_bf16 v[98:101], v[184:187], v[210:213], v[98:101]
	v_mfma_f32_16x16x32_bf16 v[84:87], v[176:179], v[218:221], v[84:87]
	v_mfma_f32_16x16x32_bf16 v[80:83], v[184:187], v[218:221], v[80:83]
	v_mfma_f32_16x16x32_bf16 v[68:71], v[176:179], v[226:229], v[68:71]
	v_mfma_f32_16x16x32_bf16 v[64:67], v[184:187], v[226:229], v[64:67]
	s_barrier
	s_setprio 0
	s_add_i32 s57, s55, s75
	s_mov_b32 m0, s57
	ds_read_b128 v[188:191], v159 offset:49152
	ds_read_b128 v[192:195], v159 offset:50176
	ds_read_b128 v[196:199], v159 offset:51200
	ds_read_b128 v[210:213], v159 offset:52224
	ds_read_b128 v[214:217], v159 offset:53248
	ds_read_b128 v[218:221], v159 offset:54272
	ds_read_b128 v[222:225], v159 offset:55296
	ds_read_b128 v[226:229], v159 offset:56320
	global_load_lds_dwordx4 v154, s[44:45]
	s_add_i32 m0, s57, 0x2000
	s_add_i32 s57, s56, s75
	global_load_lds_dwordx4 v155, s[44:45]
	s_add_u32 s44, s44, 0x80080
	s_addc_u32 s45, s45, 0
	s_mov_b32 m0, s57
	s_nop 0
	global_load_lds_dwordx4 v142, s[44:45]
	s_add_i32 m0, s57, 0x2000
	s_nop 0
	global_load_lds_dwordx4 v138, s[44:45]
	s_mov_b32 m0, s79
	s_nop 0
	global_load_lds_dwordx4 v156, s[52:53]
	s_mov_b32 m0, s81
	s_nop 0
	global_load_lds_dwordx4 v157, s[52:53]
	s_waitcnt vmcnt(8)
	s_waitcnt lgkmcnt(0)
	s_setprio 1
	s_barrier
	v_mfma_f32_16x16x32_bf16 v[60:63], v[130:133], v[188:191], v[60:63]
	v_mfma_f32_16x16x32_bf16 v[56:59], v[164:167], v[188:191], v[56:59]
	v_mfma_f32_16x16x32_bf16 v[44:47], v[130:133], v[196:199], v[44:47]
	v_mfma_f32_16x16x32_bf16 v[40:43], v[164:167], v[196:199], v[40:43]
	v_mfma_f32_16x16x32_bf16 v[28:31], v[130:133], v[214:217], v[28:31]
	v_mfma_f32_16x16x32_bf16 v[24:27], v[164:167], v[214:217], v[24:27]
	v_mfma_f32_16x16x32_bf16 v[12:15], v[130:133], v[222:225], v[12:15]
	v_mfma_f32_16x16x32_bf16 v[8:11], v[164:167], v[222:225], v[8:11]
	v_mfma_f32_16x16x32_bf16 v[60:63], v[160:163], v[192:195], v[60:63]
	v_mfma_f32_16x16x32_bf16 v[56:59], v[168:171], v[192:195], v[56:59]
	v_mfma_f32_16x16x32_bf16 v[44:47], v[160:163], v[210:213], v[44:47]
	v_mfma_f32_16x16x32_bf16 v[40:43], v[168:171], v[210:213], v[40:43]
	v_mfma_f32_16x16x32_bf16 v[28:31], v[160:163], v[218:221], v[28:31]
	v_mfma_f32_16x16x32_bf16 v[24:27], v[168:171], v[218:221], v[24:27]
	v_mfma_f32_16x16x32_bf16 v[12:15], v[160:163], v[226:229], v[12:15]
	v_mfma_f32_16x16x32_bf16 v[8:11], v[168:171], v[226:229], v[8:11]
	v_mfma_f32_16x16x32_bf16 v[52:55], v[172:175], v[188:191], v[52:55]
	v_mfma_f32_16x16x32_bf16 v[48:51], v[180:183], v[188:191], v[48:51]
	v_mfma_f32_16x16x32_bf16 v[36:39], v[172:175], v[196:199], v[36:39]
	v_mfma_f32_16x16x32_bf16 v[32:35], v[180:183], v[196:199], v[32:35]
	v_mfma_f32_16x16x32_bf16 v[20:23], v[172:175], v[214:217], v[20:23]
	v_mfma_f32_16x16x32_bf16 v[16:19], v[180:183], v[214:217], v[16:19]
	v_mfma_f32_16x16x32_bf16 v[4:7], v[172:175], v[222:225], v[4:7]
	v_mfma_f32_16x16x32_bf16 v[0:3], v[180:183], v[222:225], v[0:3]
	v_mfma_f32_16x16x32_bf16 v[52:55], v[176:179], v[192:195], v[52:55]
	v_mfma_f32_16x16x32_bf16 v[48:51], v[184:187], v[192:195], v[48:51]
	v_mfma_f32_16x16x32_bf16 v[36:39], v[176:179], v[210:213], v[36:39]
	v_mfma_f32_16x16x32_bf16 v[32:35], v[184:187], v[210:213], v[32:35]
	v_mfma_f32_16x16x32_bf16 v[20:23], v[176:179], v[218:221], v[20:23]
	v_mfma_f32_16x16x32_bf16 v[16:19], v[184:187], v[218:221], v[16:19]
	v_mfma_f32_16x16x32_bf16 v[4:7], v[176:179], v[226:229], v[4:7]
	v_mfma_f32_16x16x32_bf16 v[0:3], v[184:187], v[226:229], v[0:3]
	s_barrier
	s_setprio 0
	s_add_i32 s54, s54, 2
	s_add_u32 s42, s42, 0x100
	s_addc_u32 s43, s43, 0
	s_add_u32 s28, s28, 0x100
	s_addc_u32 s33, s33, 0
	s_cmp_gt_u32 s54, 29
	s_cbranch_scc0 .LBB0_352
	v_mov_b32_e32 v243, 1
	v_readlane_b32 s6, v251, 54
	v_readlane_b32 s7, v251, 55
	s_and_b64 vcc, exec, s[6:7]
	s_cbranch_vccz .LBB0_355
	s_barrier

.LBB0_636:
	s_add_u32 s56, s68, 0xfffe0080
	s_addc_u32 s57, s69, -1
	s_add_i32 s58, 0, 0x10000
	s_cmp_eq_u32 s55, 4
	s_cselect_b32 s85, s35, s57
	s_cselect_b32 s84, s43, s56
	v_add_u32_e32 v145, s58, v142
	s_cselect_b32 s83, s31, s54
	s_cselect_b32 s82, s50, s51
	s_add_i32 s59, 0, 0x14000
	ds_read_b128 v[146:149], v145
	ds_read_b128 v[150:153], v145 offset:1024
	ds_read_b128 v[158:161], v145 offset:2048
	ds_read_b128 v[162:165], v145 offset:3072
	v_add_u32_e32 v145, s59, v142
	ds_read_b128 v[166:169], v145
	ds_read_b128 v[170:173], v145 offset:1024
	ds_read_b128 v[174:177], v145 offset:2048
	ds_read_b128 v[178:181], v145 offset:3072
	s_add_i32 m0, s10, 0xc000
	ds_read_b128 v[182:185], v144
	ds_read_b128 v[186:189], v144 offset:1024
	ds_read_b128 v[190:193], v144 offset:2048
	ds_read_b128 v[194:197], v144 offset:3072
	ds_read_b128 v[210:213], v144 offset:4096
	ds_read_b128 v[214:217], v144 offset:5120
	ds_read_b128 v[218:221], v144 offset:6144
	ds_read_b128 v[222:225], v144 offset:7168
	global_load_lds_dwordx4 v136, s[68:69]
	s_add_i32 m0, s10, 0xe000
	s_nop 0
	global_load_lds_dwordx4 v138, s[68:69]
	s_waitcnt vmcnt(8)
	s_waitcnt lgkmcnt(0)
	s_setprio 1
	s_barrier
	v_mfma_f32_16x16x32_bf16 v[126:129], v[146:149], v[182:185], v[126:129]
	v_mfma_f32_16x16x32_bf16 v[122:125], v[158:161], v[182:185], v[122:125]
	v_mfma_f32_16x16x32_bf16 v[118:121], v[146:149], v[190:193], v[118:121]
	v_mfma_f32_16x16x32_bf16 v[114:117], v[158:161], v[190:193], v[114:117]
	v_mfma_f32_16x16x32_bf16 v[102:105], v[146:149], v[210:213], v[102:105]
	v_mfma_f32_16x16x32_bf16 v[98:101], v[158:161], v[210:213], v[98:101]
	v_mfma_f32_16x16x32_bf16 v[84:87], v[146:149], v[218:221], v[84:87]
	v_mfma_f32_16x16x32_bf16 v[80:83], v[158:161], v[218:221], v[80:83]
	v_mfma_f32_16x16x32_bf16 v[126:129], v[150:153], v[186:189], v[126:129]
	v_mfma_f32_16x16x32_bf16 v[122:125], v[162:165], v[186:189], v[122:125]
	v_mfma_f32_16x16x32_bf16 v[118:121], v[150:153], v[194:197], v[118:121]
	v_mfma_f32_16x16x32_bf16 v[114:117], v[162:165], v[194:197], v[114:117]
	v_mfma_f32_16x16x32_bf16 v[102:105], v[150:153], v[214:217], v[102:105]
	v_mfma_f32_16x16x32_bf16 v[98:101], v[162:165], v[214:217], v[98:101]
	v_mfma_f32_16x16x32_bf16 v[84:87], v[150:153], v[222:225], v[84:87]
	v_mfma_f32_16x16x32_bf16 v[80:83], v[162:165], v[222:225], v[80:83]
	v_mfma_f32_16x16x32_bf16 v[110:113], v[166:169], v[182:185], v[110:113]
	v_mfma_f32_16x16x32_bf16 v[106:109], v[174:177], v[182:185], v[106:109]
	v_mfma_f32_16x16x32_bf16 v[92:95], v[166:169], v[190:193], v[92:95]
	v_mfma_f32_16x16x32_bf16 v[88:91], v[174:177], v[190:193], v[88:91]
	v_mfma_f32_16x16x32_bf16 v[76:79], v[166:169], v[210:213], v[76:79]
	v_mfma_f32_16x16x32_bf16 v[72:75], v[174:177], v[210:213], v[72:75]
	v_mfma_f32_16x16x32_bf16 v[68:71], v[166:169], v[218:221], v[68:71]
	v_mfma_f32_16x16x32_bf16 v[64:67], v[174:177], v[218:221], v[64:67]
	v_mfma_f32_16x16x32_bf16 v[110:113], v[170:173], v[186:189], v[110:113]
	v_mfma_f32_16x16x32_bf16 v[106:109], v[178:181], v[186:189], v[106:109]
	v_mfma_f32_16x16x32_bf16 v[92:95], v[170:173], v[194:197], v[92:95]
	v_mfma_f32_16x16x32_bf16 v[88:91], v[178:181], v[194:197], v[88:91]
	v_mfma_f32_16x16x32_bf16 v[76:79], v[170:173], v[214:217], v[76:79]
	v_mfma_f32_16x16x32_bf16 v[72:75], v[178:181], v[214:217], v[72:75]
	v_mfma_f32_16x16x32_bf16 v[68:71], v[170:173], v[222:225], v[68:71]
	v_mfma_f32_16x16x32_bf16 v[64:67], v[178:181], v[222:225], v[64:67]
	s_barrier
	s_setprio 0
	s_add_i32 s56, s58, s75
	s_mov_b32 m0, s56
	ds_read_b128 v[182:185], v144 offset:16384
	ds_read_b128 v[186:189], v144 offset:17408
	ds_read_b128 v[190:193], v144 offset:18432
	ds_read_b128 v[194:197], v144 offset:19456
	ds_read_b128 v[210:213], v144 offset:20480
	ds_read_b128 v[214:217], v144 offset:21504
	ds_read_b128 v[218:221], v144 offset:22528
	ds_read_b128 v[222:225], v144 offset:23552
	global_load_lds_dwordx4 v96, s[82:83]
	s_add_i32 m0, s56, 0x2000
	s_add_u32 s56, s82, 0x20000
	s_addc_u32 s57, s83, 0
	s_add_i32 s58, s59, s75
	global_load_lds_dwordx4 v130, s[82:83]
	s_mov_b32 m0, s58
	s_nop 0
	global_load_lds_dwordx4 v96, s[56:57]
	s_add_i32 m0, s58, 0x2000
	s_nop 0
	global_load_lds_dwordx4 v130, s[56:57]
	s_mov_b32 m0, s10
	s_nop 0
	global_load_lds_dwordx4 v134, s[84:85]
	s_mov_b32 m0, s12
	s_nop 0
	global_load_lds_dwordx4 v132, s[84:85]
	s_waitcnt vmcnt(8)
	v_mov_b32_e32 v243, 0
	s_waitcnt lgkmcnt(0)
	s_setprio 1
	s_barrier
	v_mfma_f32_16x16x32_bf16 v[60:63], v[146:149], v[182:185], v[60:63]
	v_mfma_f32_16x16x32_bf16 v[56:59], v[158:161], v[182:185], v[56:59]
	v_mfma_f32_16x16x32_bf16 v[52:55], v[146:149], v[190:193], v[52:55]
	v_mfma_f32_16x16x32_bf16 v[48:51], v[158:161], v[190:193], v[48:51]
	v_mfma_f32_16x16x32_bf16 v[36:39], v[146:149], v[210:213], v[36:39]
	v_mfma_f32_16x16x32_bf16 v[32:35], v[158:161], v[210:213], v[32:35]
	v_mfma_f32_16x16x32_bf16 v[20:23], v[146:149], v[218:221], v[20:23]
	v_mfma_f32_16x16x32_bf16 v[16:19], v[158:161], v[218:221], v[16:19]
	v_mfma_f32_16x16x32_bf16 v[60:63], v[150:153], v[186:189], v[60:63]
	v_mfma_f32_16x16x32_bf16 v[56:59], v[162:165], v[186:189], v[56:59]
	v_mfma_f32_16x16x32_bf16 v[52:55], v[150:153], v[194:197], v[52:55]
	v_mfma_f32_16x16x32_bf16 v[48:51], v[162:165], v[194:197], v[48:51]
	v_mfma_f32_16x16x32_bf16 v[36:39], v[150:153], v[214:217], v[36:39]
	v_mfma_f32_16x16x32_bf16 v[32:35], v[162:165], v[214:217], v[32:35]
	v_mfma_f32_16x16x32_bf16 v[20:23], v[150:153], v[222:225], v[20:23]
	v_mfma_f32_16x16x32_bf16 v[16:19], v[162:165], v[222:225], v[16:19]
	v_mfma_f32_16x16x32_bf16 v[44:47], v[166:169], v[182:185], v[44:47]
	v_mfma_f32_16x16x32_bf16 v[40:43], v[174:177], v[182:185], v[40:43]
	v_mfma_f32_16x16x32_bf16 v[28:31], v[166:169], v[190:193], v[28:31]
	v_mfma_f32_16x16x32_bf16 v[24:27], v[174:177], v[190:193], v[24:27]
	v_mfma_f32_16x16x32_bf16 v[12:15], v[166:169], v[210:213], v[12:15]
	v_mfma_f32_16x16x32_bf16 v[8:11], v[174:177], v[210:213], v[8:11]
	v_mfma_f32_16x16x32_bf16 v[4:7], v[166:169], v[218:221], v[4:7]
	v_mfma_f32_16x16x32_bf16 v[0:3], v[174:177], v[218:221], v[0:3]
	v_mfma_f32_16x16x32_bf16 v[44:47], v[170:173], v[186:189], v[44:47]
	v_mfma_f32_16x16x32_bf16 v[40:43], v[178:181], v[186:189], v[40:43]
	v_mfma_f32_16x16x32_bf16 v[28:31], v[170:173], v[194:197], v[28:31]
	v_mfma_f32_16x16x32_bf16 v[24:27], v[178:181], v[194:197], v[24:27]
	v_mfma_f32_16x16x32_bf16 v[12:15], v[170:173], v[214:217], v[12:15]
	v_mfma_f32_16x16x32_bf16 v[8:11], v[178:181], v[214:217], v[8:11]
	v_mfma_f32_16x16x32_bf16 v[4:7], v[170:173], v[222:225], v[4:7]
	v_mfma_f32_16x16x32_bf16 v[0:3], v[178:181], v[222:225], v[0:3]
	s_barrier
	s_setprio 0
	s_add_i32 s58, 0, 0x18000
	v_add_u32_e32 v145, s58, v142
	s_add_i32 s59, 0, 0x1c000
	ds_read_b128 v[146:149], v145
	ds_read_b128 v[150:153], v145 offset:1024
	ds_read_b128 v[158:161], v145 offset:2048
	ds_read_b128 v[162:165], v145 offset:3072
	v_add_u32_e32 v145, s59, v142
	ds_read_b128 v[166:169], v145
	ds_read_b128 v[170:173], v145 offset:1024
	ds_read_b128 v[174:177], v145 offset:2048
	ds_read_b128 v[178:181], v145 offset:3072
	s_add_u32 s56, s84, 0x20000
	s_addc_u32 s57, s85, 0
	s_mov_b32 m0, s18
	ds_read_b128 v[182:185], v144 offset:32768
	ds_read_b128 v[186:189], v144 offset:33792
	ds_read_b128 v[190:193], v144 offset:34816
	ds_read_b128 v[194:197], v144 offset:35840
	ds_read_b128 v[210:213], v144 offset:36864
	ds_read_b128 v[214:217], v144 offset:37888
	ds_read_b128 v[218:221], v144 offset:38912
	ds_read_b128 v[222:225], v144 offset:39936
	global_load_lds_dwordx4 v134, s[56:57]
	s_mov_b32 m0, s20
	s_nop 0
	global_load_lds_dwordx4 v132, s[56:57]
	s_waitcnt vmcnt(8)
	s_waitcnt lgkmcnt(0)
	s_setprio 1
	s_barrier
	v_mfma_f32_16x16x32_bf16 v[126:129], v[146:149], v[182:185], v[126:129]
	v_mfma_f32_16x16x32_bf16 v[122:125], v[158:161], v[182:185], v[122:125]
	v_mfma_f32_16x16x32_bf16 v[118:121], v[146:149], v[190:193], v[118:121]
	v_mfma_f32_16x16x32_bf16 v[114:117], v[158:161], v[190:193], v[114:117]
	v_mfma_f32_16x16x32_bf16 v[102:105], v[146:149], v[210:213], v[102:105]
	v_mfma_f32_16x16x32_bf16 v[98:101], v[158:161], v[210:213], v[98:101]
	v_mfma_f32_16x16x32_bf16 v[84:87], v[146:149], v[218:221], v[84:87]
	v_mfma_f32_16x16x32_bf16 v[80:83], v[158:161], v[218:221], v[80:83]
	v_mfma_f32_16x16x32_bf16 v[126:129], v[150:153], v[186:189], v[126:129]
	v_mfma_f32_16x16x32_bf16 v[122:125], v[162:165], v[186:189], v[122:125]
	v_mfma_f32_16x16x32_bf16 v[118:121], v[150:153], v[194:197], v[118:121]
	v_mfma_f32_16x16x32_bf16 v[114:117], v[162:165], v[194:197], v[114:117]
	v_mfma_f32_16x16x32_bf16 v[102:105], v[150:153], v[214:217], v[102:105]
	v_mfma_f32_16x16x32_bf16 v[98:101], v[162:165], v[214:217], v[98:101]
	v_mfma_f32_16x16x32_bf16 v[84:87], v[150:153], v[222:225], v[84:87]
	v_mfma_f32_16x16x32_bf16 v[80:83], v[162:165], v[222:225], v[80:83]
	v_mfma_f32_16x16x32_bf16 v[110:113], v[166:169], v[182:185], v[110:113]
	v_mfma_f32_16x16x32_bf16 v[106:109], v[174:177], v[182:185], v[106:109]
	v_mfma_f32_16x16x32_bf16 v[92:95], v[166:169], v[190:193], v[92:95]
	v_mfma_f32_16x16x32_bf16 v[88:91], v[174:177], v[190:193], v[88:91]
	v_mfma_f32_16x16x32_bf16 v[76:79], v[166:169], v[210:213], v[76:79]
	v_mfma_f32_16x16x32_bf16 v[72:75], v[174:177], v[210:213], v[72:75]
	v_mfma_f32_16x16x32_bf16 v[68:71], v[166:169], v[218:221], v[68:71]
	v_mfma_f32_16x16x32_bf16 v[64:67], v[174:177], v[218:221], v[64:67]
	v_mfma_f32_16x16x32_bf16 v[110:113], v[170:173], v[186:189], v[110:113]
	v_mfma_f32_16x16x32_bf16 v[106:109], v[178:181], v[186:189], v[106:109]
	v_mfma_f32_16x16x32_bf16 v[92:95], v[170:173], v[194:197], v[92:95]
	v_mfma_f32_16x16x32_bf16 v[88:91], v[178:181], v[194:197], v[88:91]
	v_mfma_f32_16x16x32_bf16 v[76:79], v[170:173], v[214:217], v[76:79]
	v_mfma_f32_16x16x32_bf16 v[72:75], v[178:181], v[214:217], v[72:75]
	v_mfma_f32_16x16x32_bf16 v[68:71], v[170:173], v[222:225], v[68:71]
	v_mfma_f32_16x16x32_bf16 v[64:67], v[178:181], v[222:225], v[64:67]
	s_barrier
	s_setprio 0
	s_add_i32 s56, s58, s75
	s_mov_b32 m0, s56
	ds_read_b128 v[182:185], v144 offset:49152
	ds_read_b128 v[186:189], v144 offset:50176
	ds_read_b128 v[190:193], v144 offset:51200
	ds_read_b128 v[194:197], v144 offset:52224
	ds_read_b128 v[210:213], v144 offset:53248
	ds_read_b128 v[214:217], v144 offset:54272
	ds_read_b128 v[218:221], v144 offset:55296
	ds_read_b128 v[222:225], v144 offset:56320
	global_load_lds_dwordx4 v155, s[82:83]
	s_add_i32 m0, s56, 0x2000
	s_add_u32 s56, s82, 0x20080
	s_addc_u32 s57, s83, 0
	s_add_i32 s58, s59, s75
	global_load_lds_dwordx4 v157, s[82:83]
	s_mov_b32 m0, s58
	s_nop 0
	global_load_lds_dwordx4 v96, s[56:57]
	s_add_i32 m0, s58, 0x2000
	s_nop 0
	global_load_lds_dwordx4 v130, s[56:57]
	s_mov_b32 m0, s26
	s_nop 0
	global_load_lds_dwordx4 v199, s[84:85]
	s_mov_b32 m0, s27
	s_nop 0
	global_load_lds_dwordx4 v203, s[84:85]
	s_waitcnt vmcnt(8)
	s_waitcnt lgkmcnt(0)
	s_setprio 1
	s_barrier
	v_mfma_f32_16x16x32_bf16 v[60:63], v[146:149], v[182:185], v[60:63]
	v_mfma_f32_16x16x32_bf16 v[56:59], v[158:161], v[182:185], v[56:59]
	v_mfma_f32_16x16x32_bf16 v[52:55], v[146:149], v[190:193], v[52:55]
	v_mfma_f32_16x16x32_bf16 v[48:51], v[158:161], v[190:193], v[48:51]
	v_mfma_f32_16x16x32_bf16 v[36:39], v[146:149], v[210:213], v[36:39]
	v_mfma_f32_16x16x32_bf16 v[32:35], v[158:161], v[210:213], v[32:35]
	v_mfma_f32_16x16x32_bf16 v[20:23], v[146:149], v[218:221], v[20:23]
	v_mfma_f32_16x16x32_bf16 v[16:19], v[158:161], v[218:221], v[16:19]
	v_mfma_f32_16x16x32_bf16 v[60:63], v[150:153], v[186:189], v[60:63]
	v_mfma_f32_16x16x32_bf16 v[56:59], v[162:165], v[186:189], v[56:59]
	v_mfma_f32_16x16x32_bf16 v[52:55], v[150:153], v[194:197], v[52:55]
	v_mfma_f32_16x16x32_bf16 v[48:51], v[162:165], v[194:197], v[48:51]
	v_mfma_f32_16x16x32_bf16 v[36:39], v[150:153], v[214:217], v[36:39]
	v_mfma_f32_16x16x32_bf16 v[32:35], v[162:165], v[214:217], v[32:35]
	v_mfma_f32_16x16x32_bf16 v[20:23], v[150:153], v[222:225], v[20:23]
	v_mfma_f32_16x16x32_bf16 v[16:19], v[162:165], v[222:225], v[16:19]
	v_mfma_f32_16x16x32_bf16 v[44:47], v[166:169], v[182:185], v[44:47]
	v_mfma_f32_16x16x32_bf16 v[40:43], v[174:177], v[182:185], v[40:43]
	v_mfma_f32_16x16x32_bf16 v[28:31], v[166:169], v[190:193], v[28:31]
	v_mfma_f32_16x16x32_bf16 v[24:27], v[174:177], v[190:193], v[24:27]
	v_mfma_f32_16x16x32_bf16 v[12:15], v[166:169], v[210:213], v[12:15]
	v_mfma_f32_16x16x32_bf16 v[8:11], v[174:177], v[210:213], v[8:11]
	v_mfma_f32_16x16x32_bf16 v[4:7], v[166:169], v[218:221], v[4:7]
	v_mfma_f32_16x16x32_bf16 v[0:3], v[174:177], v[218:221], v[0:3]
	v_mfma_f32_16x16x32_bf16 v[44:47], v[170:173], v[186:189], v[44:47]
	v_mfma_f32_16x16x32_bf16 v[40:43], v[178:181], v[186:189], v[40:43]
	v_mfma_f32_16x16x32_bf16 v[28:31], v[170:173], v[194:197], v[28:31]
	v_mfma_f32_16x16x32_bf16 v[24:27], v[178:181], v[194:197], v[24:27]
	v_mfma_f32_16x16x32_bf16 v[12:15], v[170:173], v[214:217], v[12:15]
	v_mfma_f32_16x16x32_bf16 v[8:11], v[178:181], v[214:217], v[8:11]
	v_mfma_f32_16x16x32_bf16 v[4:7], v[170:173], v[222:225], v[4:7]
	v_mfma_f32_16x16x32_bf16 v[0:3], v[178:181], v[222:225], v[0:3]
	s_barrier
	s_setprio 0
	s_add_i32 s55, s55, 2
	s_add_u32 s68, s68, 0x100
	s_addc_u32 s69, s69, 0
	s_add_u32 s51, s51, 0x100
	s_addc_u32 s54, s54, 0
	s_cmp_gt_u32 s55, 5
	s_cbranch_scc0 .LBB0_636
	v_mov_b32_e32 v243, 1
	v_readlane_b32 s6, v251, 54
	v_readlane_b32 s7, v251, 55
	s_and_b64 vcc, exec, s[6:7]
	s_cbranch_vccz .LBB0_639
	s_barrier

.LBB0_656:
	s_add_u32 s58, s68, 0xfffe0080
	s_addc_u32 s59, s69, -1
	s_add_i32 s61, 0, 0x10000
	s_cmp_eq_u32 s57, 4
	s_cselect_b32 s85, s43, s59
	s_cselect_b32 s84, s51, s58
	v_add_u32_e32 v145, s61, v142
	s_cselect_b32 s83, s31, s56
	s_cselect_b32 s82, s54, s55
	s_add_i32 s62, 0, 0x14000
	ds_read_b128 v[146:149], v145
	ds_read_b128 v[150:153], v145 offset:1024
	ds_read_b128 v[158:161], v145 offset:2048
	ds_read_b128 v[162:165], v145 offset:3072
	v_add_u32_e32 v145, s62, v142
	ds_read_b128 v[166:169], v145
	ds_read_b128 v[170:173], v145 offset:1024
	ds_read_b128 v[174:177], v145 offset:2048
	ds_read_b128 v[178:181], v145 offset:3072
	s_add_i32 m0, s18, 0xc000
	ds_read_b128 v[182:185], v144
	ds_read_b128 v[186:189], v144 offset:1024
	ds_read_b128 v[190:193], v144 offset:2048
	ds_read_b128 v[194:197], v144 offset:3072
	ds_read_b128 v[210:213], v144 offset:4096
	ds_read_b128 v[214:217], v144 offset:5120
	ds_read_b128 v[218:221], v144 offset:6144
	ds_read_b128 v[222:225], v144 offset:7168
	global_load_lds_dwordx4 v136, s[68:69]
	s_add_i32 m0, s18, 0xe000
	s_nop 0
	global_load_lds_dwordx4 v138, s[68:69]
	s_waitcnt vmcnt(8)
	s_waitcnt lgkmcnt(0)
	s_setprio 1
	s_barrier
	v_mfma_f32_16x16x32_bf16 v[126:129], v[146:149], v[182:185], v[126:129]
	v_mfma_f32_16x16x32_bf16 v[122:125], v[158:161], v[182:185], v[122:125]
	v_mfma_f32_16x16x32_bf16 v[118:121], v[146:149], v[190:193], v[118:121]
	v_mfma_f32_16x16x32_bf16 v[114:117], v[158:161], v[190:193], v[114:117]
	v_mfma_f32_16x16x32_bf16 v[102:105], v[146:149], v[210:213], v[102:105]
	v_mfma_f32_16x16x32_bf16 v[98:101], v[158:161], v[210:213], v[98:101]
	v_mfma_f32_16x16x32_bf16 v[84:87], v[146:149], v[218:221], v[84:87]
	v_mfma_f32_16x16x32_bf16 v[80:83], v[158:161], v[218:221], v[80:83]
	v_mfma_f32_16x16x32_bf16 v[126:129], v[150:153], v[186:189], v[126:129]
	v_mfma_f32_16x16x32_bf16 v[122:125], v[162:165], v[186:189], v[122:125]
	v_mfma_f32_16x16x32_bf16 v[118:121], v[150:153], v[194:197], v[118:121]
	v_mfma_f32_16x16x32_bf16 v[114:117], v[162:165], v[194:197], v[114:117]
	v_mfma_f32_16x16x32_bf16 v[102:105], v[150:153], v[214:217], v[102:105]
	v_mfma_f32_16x16x32_bf16 v[98:101], v[162:165], v[214:217], v[98:101]
	v_mfma_f32_16x16x32_bf16 v[84:87], v[150:153], v[222:225], v[84:87]
	v_mfma_f32_16x16x32_bf16 v[80:83], v[162:165], v[222:225], v[80:83]
	v_mfma_f32_16x16x32_bf16 v[110:113], v[166:169], v[182:185], v[110:113]
	v_mfma_f32_16x16x32_bf16 v[106:109], v[174:177], v[182:185], v[106:109]
	v_mfma_f32_16x16x32_bf16 v[92:95], v[166:169], v[190:193], v[92:95]
	v_mfma_f32_16x16x32_bf16 v[88:91], v[174:177], v[190:193], v[88:91]
	v_mfma_f32_16x16x32_bf16 v[76:79], v[166:169], v[210:213], v[76:79]
	v_mfma_f32_16x16x32_bf16 v[72:75], v[174:177], v[210:213], v[72:75]
	v_mfma_f32_16x16x32_bf16 v[68:71], v[166:169], v[218:221], v[68:71]
	v_mfma_f32_16x16x32_bf16 v[64:67], v[174:177], v[218:221], v[64:67]
	v_mfma_f32_16x16x32_bf16 v[110:113], v[170:173], v[186:189], v[110:113]
	v_mfma_f32_16x16x32_bf16 v[106:109], v[178:181], v[186:189], v[106:109]
	v_mfma_f32_16x16x32_bf16 v[92:95], v[170:173], v[194:197], v[92:95]
	v_mfma_f32_16x16x32_bf16 v[88:91], v[178:181], v[194:197], v[88:91]
	v_mfma_f32_16x16x32_bf16 v[76:79], v[170:173], v[214:217], v[76:79]
	v_mfma_f32_16x16x32_bf16 v[72:75], v[178:181], v[214:217], v[72:75]
	v_mfma_f32_16x16x32_bf16 v[68:71], v[170:173], v[222:225], v[68:71]
	v_mfma_f32_16x16x32_bf16 v[64:67], v[178:181], v[222:225], v[64:67]
	s_barrier
	s_setprio 0
	s_add_i32 s58, s61, s75
	s_mov_b32 m0, s58
	ds_read_b128 v[182:185], v144 offset:16384
	ds_read_b128 v[186:189], v144 offset:17408
	ds_read_b128 v[190:193], v144 offset:18432
	ds_read_b128 v[194:197], v144 offset:19456
	ds_read_b128 v[210:213], v144 offset:20480
	ds_read_b128 v[214:217], v144 offset:21504
	ds_read_b128 v[218:221], v144 offset:22528
	ds_read_b128 v[222:225], v144 offset:23552
	global_load_lds_dwordx4 v96, s[82:83]
	s_add_i32 m0, s58, 0x2000
	s_add_u32 s58, s82, 0x20000
	s_addc_u32 s59, s83, 0
	s_add_i32 s61, s62, s75
	global_load_lds_dwordx4 v130, s[82:83]
	s_mov_b32 m0, s61
	s_nop 0
	global_load_lds_dwordx4 v96, s[58:59]
	s_add_i32 m0, s61, 0x2000
	s_nop 0
	global_load_lds_dwordx4 v130, s[58:59]
	s_mov_b32 m0, s18
	s_nop 0
	global_load_lds_dwordx4 v134, s[84:85]
	s_mov_b32 m0, s20
	s_nop 0
	global_load_lds_dwordx4 v132, s[84:85]
	s_waitcnt vmcnt(8)
	v_mov_b32_e32 v243, 0
	s_waitcnt lgkmcnt(0)
	s_setprio 1
	s_barrier
	v_mfma_f32_16x16x32_bf16 v[60:63], v[146:149], v[182:185], v[60:63]
	v_mfma_f32_16x16x32_bf16 v[56:59], v[158:161], v[182:185], v[56:59]
	v_mfma_f32_16x16x32_bf16 v[52:55], v[146:149], v[190:193], v[52:55]
	v_mfma_f32_16x16x32_bf16 v[48:51], v[158:161], v[190:193], v[48:51]
	v_mfma_f32_16x16x32_bf16 v[36:39], v[146:149], v[210:213], v[36:39]
	v_mfma_f32_16x16x32_bf16 v[32:35], v[158:161], v[210:213], v[32:35]
	v_mfma_f32_16x16x32_bf16 v[20:23], v[146:149], v[218:221], v[20:23]
	v_mfma_f32_16x16x32_bf16 v[16:19], v[158:161], v[218:221], v[16:19]
	v_mfma_f32_16x16x32_bf16 v[60:63], v[150:153], v[186:189], v[60:63]
	v_mfma_f32_16x16x32_bf16 v[56:59], v[162:165], v[186:189], v[56:59]
	v_mfma_f32_16x16x32_bf16 v[52:55], v[150:153], v[194:197], v[52:55]
	v_mfma_f32_16x16x32_bf16 v[48:51], v[162:165], v[194:197], v[48:51]
	v_mfma_f32_16x16x32_bf16 v[36:39], v[150:153], v[214:217], v[36:39]
	v_mfma_f32_16x16x32_bf16 v[32:35], v[162:165], v[214:217], v[32:35]
	v_mfma_f32_16x16x32_bf16 v[20:23], v[150:153], v[222:225], v[20:23]
	v_mfma_f32_16x16x32_bf16 v[16:19], v[162:165], v[222:225], v[16:19]
	v_mfma_f32_16x16x32_bf16 v[44:47], v[166:169], v[182:185], v[44:47]
	v_mfma_f32_16x16x32_bf16 v[40:43], v[174:177], v[182:185], v[40:43]
	v_mfma_f32_16x16x32_bf16 v[28:31], v[166:169], v[190:193], v[28:31]
	v_mfma_f32_16x16x32_bf16 v[24:27], v[174:177], v[190:193], v[24:27]
	v_mfma_f32_16x16x32_bf16 v[12:15], v[166:169], v[210:213], v[12:15]
	v_mfma_f32_16x16x32_bf16 v[8:11], v[174:177], v[210:213], v[8:11]
	v_mfma_f32_16x16x32_bf16 v[4:7], v[166:169], v[218:221], v[4:7]
	v_mfma_f32_16x16x32_bf16 v[0:3], v[174:177], v[218:221], v[0:3]
	v_mfma_f32_16x16x32_bf16 v[44:47], v[170:173], v[186:189], v[44:47]
	v_mfma_f32_16x16x32_bf16 v[40:43], v[178:181], v[186:189], v[40:43]
	v_mfma_f32_16x16x32_bf16 v[28:31], v[170:173], v[194:197], v[28:31]
	v_mfma_f32_16x16x32_bf16 v[24:27], v[178:181], v[194:197], v[24:27]
	v_mfma_f32_16x16x32_bf16 v[12:15], v[170:173], v[214:217], v[12:15]
	v_mfma_f32_16x16x32_bf16 v[8:11], v[178:181], v[214:217], v[8:11]
	v_mfma_f32_16x16x32_bf16 v[4:7], v[170:173], v[222:225], v[4:7]
	v_mfma_f32_16x16x32_bf16 v[0:3], v[178:181], v[222:225], v[0:3]
	s_barrier
	s_setprio 0
	s_add_i32 s61, 0, 0x18000
	v_add_u32_e32 v145, s61, v142
	s_add_i32 s62, 0, 0x1c000
	ds_read_b128 v[146:149], v145
	ds_read_b128 v[150:153], v145 offset:1024
	ds_read_b128 v[158:161], v145 offset:2048
	ds_read_b128 v[162:165], v145 offset:3072
	v_add_u32_e32 v145, s62, v142
	ds_read_b128 v[166:169], v145
	ds_read_b128 v[170:173], v145 offset:1024
	ds_read_b128 v[174:177], v145 offset:2048
	ds_read_b128 v[178:181], v145 offset:3072
	s_add_u32 s58, s84, 0x20000
	s_addc_u32 s59, s85, 0
	s_mov_b32 m0, s26
	ds_read_b128 v[182:185], v144 offset:32768
	ds_read_b128 v[186:189], v144 offset:33792
	ds_read_b128 v[190:193], v144 offset:34816
	ds_read_b128 v[194:197], v144 offset:35840
	ds_read_b128 v[210:213], v144 offset:36864
	ds_read_b128 v[214:217], v144 offset:37888
	ds_read_b128 v[218:221], v144 offset:38912
	ds_read_b128 v[222:225], v144 offset:39936
	global_load_lds_dwordx4 v134, s[58:59]
	s_mov_b32 m0, s27
	s_nop 0
	global_load_lds_dwordx4 v132, s[58:59]
	s_waitcnt vmcnt(8)
	s_waitcnt lgkmcnt(0)
	s_setprio 1
	s_barrier
	v_mfma_f32_16x16x32_bf16 v[126:129], v[146:149], v[182:185], v[126:129]
	v_mfma_f32_16x16x32_bf16 v[122:125], v[158:161], v[182:185], v[122:125]
	v_mfma_f32_16x16x32_bf16 v[118:121], v[146:149], v[190:193], v[118:121]
	v_mfma_f32_16x16x32_bf16 v[114:117], v[158:161], v[190:193], v[114:117]
	v_mfma_f32_16x16x32_bf16 v[102:105], v[146:149], v[210:213], v[102:105]
	v_mfma_f32_16x16x32_bf16 v[98:101], v[158:161], v[210:213], v[98:101]
	v_mfma_f32_16x16x32_bf16 v[84:87], v[146:149], v[218:221], v[84:87]
	v_mfma_f32_16x16x32_bf16 v[80:83], v[158:161], v[218:221], v[80:83]
	v_mfma_f32_16x16x32_bf16 v[126:129], v[150:153], v[186:189], v[126:129]
	v_mfma_f32_16x16x32_bf16 v[122:125], v[162:165], v[186:189], v[122:125]
	v_mfma_f32_16x16x32_bf16 v[118:121], v[150:153], v[194:197], v[118:121]
	v_mfma_f32_16x16x32_bf16 v[114:117], v[162:165], v[194:197], v[114:117]
	v_mfma_f32_16x16x32_bf16 v[102:105], v[150:153], v[214:217], v[102:105]
	v_mfma_f32_16x16x32_bf16 v[98:101], v[162:165], v[214:217], v[98:101]
	v_mfma_f32_16x16x32_bf16 v[84:87], v[150:153], v[222:225], v[84:87]
	v_mfma_f32_16x16x32_bf16 v[80:83], v[162:165], v[222:225], v[80:83]
	v_mfma_f32_16x16x32_bf16 v[110:113], v[166:169], v[182:185], v[110:113]
	v_mfma_f32_16x16x32_bf16 v[106:109], v[174:177], v[182:185], v[106:109]
	v_mfma_f32_16x16x32_bf16 v[92:95], v[166:169], v[190:193], v[92:95]
	v_mfma_f32_16x16x32_bf16 v[88:91], v[174:177], v[190:193], v[88:91]
	v_mfma_f32_16x16x32_bf16 v[76:79], v[166:169], v[210:213], v[76:79]
	v_mfma_f32_16x16x32_bf16 v[72:75], v[174:177], v[210:213], v[72:75]
	v_mfma_f32_16x16x32_bf16 v[68:71], v[166:169], v[218:221], v[68:71]
	v_mfma_f32_16x16x32_bf16 v[64:67], v[174:177], v[218:221], v[64:67]
	v_mfma_f32_16x16x32_bf16 v[110:113], v[170:173], v[186:189], v[110:113]
	v_mfma_f32_16x16x32_bf16 v[106:109], v[178:181], v[186:189], v[106:109]
	v_mfma_f32_16x16x32_bf16 v[92:95], v[170:173], v[194:197], v[92:95]
	v_mfma_f32_16x16x32_bf16 v[88:91], v[178:181], v[194:197], v[88:91]
	v_mfma_f32_16x16x32_bf16 v[76:79], v[170:173], v[214:217], v[76:79]
	v_mfma_f32_16x16x32_bf16 v[72:75], v[178:181], v[214:217], v[72:75]
	v_mfma_f32_16x16x32_bf16 v[68:71], v[170:173], v[222:225], v[68:71]
	v_mfma_f32_16x16x32_bf16 v[64:67], v[178:181], v[222:225], v[64:67]
	s_barrier
	s_setprio 0
	s_add_i32 s58, s61, s75
	s_mov_b32 m0, s58
	ds_read_b128 v[182:185], v144 offset:49152
	ds_read_b128 v[186:189], v144 offset:50176
	ds_read_b128 v[190:193], v144 offset:51200
	ds_read_b128 v[194:197], v144 offset:52224
	ds_read_b128 v[210:213], v144 offset:53248
	ds_read_b128 v[214:217], v144 offset:54272
	ds_read_b128 v[218:221], v144 offset:55296
	ds_read_b128 v[222:225], v144 offset:56320
	global_load_lds_dwordx4 v155, s[82:83]
	s_add_i32 m0, s58, 0x2000
	s_add_u32 s58, s82, 0x20080
	s_addc_u32 s59, s83, 0
	s_add_i32 s61, s62, s75
	global_load_lds_dwordx4 v157, s[82:83]
	s_mov_b32 m0, s61
	s_nop 0
	global_load_lds_dwordx4 v96, s[58:59]
	s_add_i32 m0, s61, 0x2000
	s_nop 0
	global_load_lds_dwordx4 v130, s[58:59]
	s_mov_b32 m0, s28
	s_nop 0
	global_load_lds_dwordx4 v199, s[84:85]
	s_mov_b32 m0, s33
	s_nop 0
	global_load_lds_dwordx4 v203, s[84:85]
	s_waitcnt vmcnt(8)
	s_waitcnt lgkmcnt(0)
	s_setprio 1
	s_barrier
	v_mfma_f32_16x16x32_bf16 v[60:63], v[146:149], v[182:185], v[60:63]
	v_mfma_f32_16x16x32_bf16 v[56:59], v[158:161], v[182:185], v[56:59]
	v_mfma_f32_16x16x32_bf16 v[52:55], v[146:149], v[190:193], v[52:55]
	v_mfma_f32_16x16x32_bf16 v[48:51], v[158:161], v[190:193], v[48:51]
	v_mfma_f32_16x16x32_bf16 v[36:39], v[146:149], v[210:213], v[36:39]
	v_mfma_f32_16x16x32_bf16 v[32:35], v[158:161], v[210:213], v[32:35]
	v_mfma_f32_16x16x32_bf16 v[20:23], v[146:149], v[218:221], v[20:23]
	v_mfma_f32_16x16x32_bf16 v[16:19], v[158:161], v[218:221], v[16:19]
	v_mfma_f32_16x16x32_bf16 v[60:63], v[150:153], v[186:189], v[60:63]
	v_mfma_f32_16x16x32_bf16 v[56:59], v[162:165], v[186:189], v[56:59]
	v_mfma_f32_16x16x32_bf16 v[52:55], v[150:153], v[194:197], v[52:55]
	v_mfma_f32_16x16x32_bf16 v[48:51], v[162:165], v[194:197], v[48:51]
	v_mfma_f32_16x16x32_bf16 v[36:39], v[150:153], v[214:217], v[36:39]
	v_mfma_f32_16x16x32_bf16 v[32:35], v[162:165], v[214:217], v[32:35]
	v_mfma_f32_16x16x32_bf16 v[20:23], v[150:153], v[222:225], v[20:23]
	v_mfma_f32_16x16x32_bf16 v[16:19], v[162:165], v[222:225], v[16:19]
	v_mfma_f32_16x16x32_bf16 v[44:47], v[166:169], v[182:185], v[44:47]
	v_mfma_f32_16x16x32_bf16 v[40:43], v[174:177], v[182:185], v[40:43]
	v_mfma_f32_16x16x32_bf16 v[28:31], v[166:169], v[190:193], v[28:31]
	v_mfma_f32_16x16x32_bf16 v[24:27], v[174:177], v[190:193], v[24:27]
	v_mfma_f32_16x16x32_bf16 v[12:15], v[166:169], v[210:213], v[12:15]
	v_mfma_f32_16x16x32_bf16 v[8:11], v[174:177], v[210:213], v[8:11]
	v_mfma_f32_16x16x32_bf16 v[4:7], v[166:169], v[218:221], v[4:7]
	v_mfma_f32_16x16x32_bf16 v[0:3], v[174:177], v[218:221], v[0:3]
	v_mfma_f32_16x16x32_bf16 v[44:47], v[170:173], v[186:189], v[44:47]
	v_mfma_f32_16x16x32_bf16 v[40:43], v[178:181], v[186:189], v[40:43]
	v_mfma_f32_16x16x32_bf16 v[28:31], v[170:173], v[194:197], v[28:31]
	v_mfma_f32_16x16x32_bf16 v[24:27], v[178:181], v[194:197], v[24:27]
	v_mfma_f32_16x16x32_bf16 v[12:15], v[170:173], v[214:217], v[12:15]
	v_mfma_f32_16x16x32_bf16 v[8:11], v[178:181], v[214:217], v[8:11]
	v_mfma_f32_16x16x32_bf16 v[4:7], v[170:173], v[222:225], v[4:7]
	v_mfma_f32_16x16x32_bf16 v[0:3], v[178:181], v[222:225], v[0:3]
	s_barrier
	s_setprio 0
	s_add_i32 s57, s57, 2
	s_add_u32 s68, s68, 0x100
	s_addc_u32 s69, s69, 0
	s_add_u32 s55, s55, 0x100
	s_addc_u32 s56, s56, 0
	s_cmp_gt_u32 s57, 5
	s_cbranch_scc0 .LBB0_656
	v_mov_b32_e32 v243, 1
	v_readlane_b32 s6, v251, 54
	v_readlane_b32 s7, v251, 55
	s_and_b64 vcc, exec, s[6:7]
	s_cbranch_vccz .LBB0_659
	s_barrier

.LBB0_1038:
	s_add_u32 s34, s44, 0xfff80080
	s_addc_u32 s35, s45, -1
	s_add_i32 s38, 0, 0x10000
	s_cmp_eq_u32 s33, 28
	s_cselect_b32 s87, s10, s35
	s_cselect_b32 s86, s12, s34
	s_cselect_b32 s85, s18, s31
	s_cselect_b32 s84, s20, s28
	s_add_i32 s39, 0, 0x14000
	v_add_u32_e32 v156, s38, v169
	v_add_u32_e32 v164, s39, v169
	ds_read_b128 v[130:133], v156
	ds_read_b128 v[134:137], v156 offset:1024
	ds_read_b128 v[152:155], v156 offset:2048
	ds_read_b128 v[156:159], v156 offset:3072
	ds_read_b128 v[160:163], v164
	ds_read_b128 v[172:175], v164 offset:1024
	ds_read_b128 v[176:179], v164 offset:2048
	ds_read_b128 v[180:183], v164 offset:3072
	s_add_i32 m0, s58, 0xc000
	ds_read_b128 v[184:187], v171
	ds_read_b128 v[188:191], v171 offset:1024
	ds_read_b128 v[192:195], v171 offset:2048
	ds_read_b128 v[196:199], v171 offset:3072
	ds_read_b128 v[202:205], v171 offset:4096
	ds_read_b128 v[210:213], v171 offset:5120
	ds_read_b128 v[214:217], v171 offset:6144
	ds_read_b128 v[218:221], v171 offset:7168
	global_load_lds_dwordx4 v148, s[44:45]
	s_add_i32 m0, s58, 0xe000
	s_nop 0
	global_load_lds_dwordx4 v150, s[44:45]
	s_waitcnt vmcnt(8)
	s_waitcnt lgkmcnt(0)
	s_setprio 1
	s_barrier
	v_mfma_f32_16x16x32_bf16 v[126:129], v[130:133], v[184:187], v[126:129]
	v_mfma_f32_16x16x32_bf16 v[122:125], v[152:155], v[184:187], v[122:125]
	v_mfma_f32_16x16x32_bf16 v[110:113], v[130:133], v[192:195], v[110:113]
	v_mfma_f32_16x16x32_bf16 v[106:109], v[152:155], v[192:195], v[106:109]
	v_mfma_f32_16x16x32_bf16 v[92:95], v[130:133], v[202:205], v[92:95]
	v_mfma_f32_16x16x32_bf16 v[88:91], v[152:155], v[202:205], v[88:91]
	v_mfma_f32_16x16x32_bf16 v[76:79], v[130:133], v[214:217], v[76:79]
	v_mfma_f32_16x16x32_bf16 v[72:75], v[152:155], v[214:217], v[72:75]
	v_mfma_f32_16x16x32_bf16 v[126:129], v[134:137], v[188:191], v[126:129]
	v_mfma_f32_16x16x32_bf16 v[122:125], v[156:159], v[188:191], v[122:125]
	v_mfma_f32_16x16x32_bf16 v[110:113], v[134:137], v[196:199], v[110:113]
	v_mfma_f32_16x16x32_bf16 v[106:109], v[156:159], v[196:199], v[106:109]
	v_mfma_f32_16x16x32_bf16 v[92:95], v[134:137], v[210:213], v[92:95]
	v_mfma_f32_16x16x32_bf16 v[88:91], v[156:159], v[210:213], v[88:91]
	v_mfma_f32_16x16x32_bf16 v[76:79], v[134:137], v[218:221], v[76:79]
	v_mfma_f32_16x16x32_bf16 v[72:75], v[156:159], v[218:221], v[72:75]
	v_mfma_f32_16x16x32_bf16 v[118:121], v[160:163], v[184:187], v[118:121]
	v_mfma_f32_16x16x32_bf16 v[114:117], v[176:179], v[184:187], v[114:117]
	v_mfma_f32_16x16x32_bf16 v[102:105], v[160:163], v[192:195], v[102:105]
	v_mfma_f32_16x16x32_bf16 v[98:101], v[176:179], v[192:195], v[98:101]
	v_mfma_f32_16x16x32_bf16 v[84:87], v[160:163], v[202:205], v[84:87]
	v_mfma_f32_16x16x32_bf16 v[80:83], v[176:179], v[202:205], v[80:83]
	v_mfma_f32_16x16x32_bf16 v[68:71], v[160:163], v[214:217], v[68:71]
	v_mfma_f32_16x16x32_bf16 v[64:67], v[176:179], v[214:217], v[64:67]
	v_mfma_f32_16x16x32_bf16 v[118:121], v[172:175], v[188:191], v[118:121]
	v_mfma_f32_16x16x32_bf16 v[114:117], v[180:183], v[188:191], v[114:117]
	v_mfma_f32_16x16x32_bf16 v[102:105], v[172:175], v[196:199], v[102:105]
	v_mfma_f32_16x16x32_bf16 v[98:101], v[180:183], v[196:199], v[98:101]
	v_mfma_f32_16x16x32_bf16 v[84:87], v[172:175], v[210:213], v[84:87]
	v_mfma_f32_16x16x32_bf16 v[80:83], v[180:183], v[210:213], v[80:83]
	v_mfma_f32_16x16x32_bf16 v[68:71], v[172:175], v[218:221], v[68:71]
	v_mfma_f32_16x16x32_bf16 v[64:67], v[180:183], v[218:221], v[64:67]
	s_barrier
	s_setprio 0
	s_add_i32 s34, s38, s75
	s_mov_b32 m0, s34
	ds_read_b128 v[184:187], v171 offset:16384
	ds_read_b128 v[188:191], v171 offset:17408
	ds_read_b128 v[192:195], v171 offset:18432
	ds_read_b128 v[196:199], v171 offset:19456
	ds_read_b128 v[202:205], v171 offset:20480
	ds_read_b128 v[210:213], v171 offset:21504
	ds_read_b128 v[214:217], v171 offset:22528
	ds_read_b128 v[218:221], v171 offset:23552
	global_load_lds_dwordx4 v96, s[84:85]
	s_add_i32 m0, s34, 0x2000
	s_add_u32 s34, s84, 0x80000
	s_addc_u32 s35, s85, 0
	s_add_i32 s38, s39, s75
	global_load_lds_dwordx4 v142, s[84:85]
	s_mov_b32 m0, s38
	s_nop 0
	global_load_lds_dwordx4 v96, s[34:35]
	s_add_i32 m0, s38, 0x2000
	s_nop 0
	global_load_lds_dwordx4 v142, s[34:35]
	s_mov_b32 m0, s58
	s_nop 0
	global_load_lds_dwordx4 v146, s[86:87]
	s_mov_b32 m0, s59
	s_nop 0
	global_load_lds_dwordx4 v144, s[86:87]
	s_waitcnt vmcnt(8)
	v_mov_b32_e32 v243, 0
	s_waitcnt lgkmcnt(0)
	s_setprio 1
	s_barrier
	v_mfma_f32_16x16x32_bf16 v[60:63], v[130:133], v[184:187], v[60:63]
	v_mfma_f32_16x16x32_bf16 v[56:59], v[152:155], v[184:187], v[56:59]
	v_mfma_f32_16x16x32_bf16 v[44:47], v[130:133], v[192:195], v[44:47]
	v_mfma_f32_16x16x32_bf16 v[40:43], v[152:155], v[192:195], v[40:43]
	v_mfma_f32_16x16x32_bf16 v[28:31], v[130:133], v[202:205], v[28:31]
	v_mfma_f32_16x16x32_bf16 v[24:27], v[152:155], v[202:205], v[24:27]
	v_mfma_f32_16x16x32_bf16 v[12:15], v[130:133], v[214:217], v[12:15]
	v_mfma_f32_16x16x32_bf16 v[8:11], v[152:155], v[214:217], v[8:11]
	v_mfma_f32_16x16x32_bf16 v[60:63], v[134:137], v[188:191], v[60:63]
	v_mfma_f32_16x16x32_bf16 v[56:59], v[156:159], v[188:191], v[56:59]
	v_mfma_f32_16x16x32_bf16 v[44:47], v[134:137], v[196:199], v[44:47]
	v_mfma_f32_16x16x32_bf16 v[40:43], v[156:159], v[196:199], v[40:43]
	v_mfma_f32_16x16x32_bf16 v[28:31], v[134:137], v[210:213], v[28:31]
	v_mfma_f32_16x16x32_bf16 v[24:27], v[156:159], v[210:213], v[24:27]
	v_mfma_f32_16x16x32_bf16 v[12:15], v[134:137], v[218:221], v[12:15]
	v_mfma_f32_16x16x32_bf16 v[8:11], v[156:159], v[218:221], v[8:11]
	v_mfma_f32_16x16x32_bf16 v[52:55], v[160:163], v[184:187], v[52:55]
	v_mfma_f32_16x16x32_bf16 v[48:51], v[176:179], v[184:187], v[48:51]
	v_mfma_f32_16x16x32_bf16 v[36:39], v[160:163], v[192:195], v[36:39]
	v_mfma_f32_16x16x32_bf16 v[32:35], v[176:179], v[192:195], v[32:35]
	v_mfma_f32_16x16x32_bf16 v[20:23], v[160:163], v[202:205], v[20:23]
	v_mfma_f32_16x16x32_bf16 v[16:19], v[176:179], v[202:205], v[16:19]
	v_mfma_f32_16x16x32_bf16 v[4:7], v[160:163], v[214:217], v[4:7]
	v_mfma_f32_16x16x32_bf16 v[0:3], v[176:179], v[214:217], v[0:3]
	v_mfma_f32_16x16x32_bf16 v[52:55], v[172:175], v[188:191], v[52:55]
	v_mfma_f32_16x16x32_bf16 v[48:51], v[180:183], v[188:191], v[48:51]
	v_mfma_f32_16x16x32_bf16 v[36:39], v[172:175], v[196:199], v[36:39]
	v_mfma_f32_16x16x32_bf16 v[32:35], v[180:183], v[196:199], v[32:35]
	v_mfma_f32_16x16x32_bf16 v[20:23], v[172:175], v[210:213], v[20:23]
	v_mfma_f32_16x16x32_bf16 v[16:19], v[180:183], v[210:213], v[16:19]
	v_mfma_f32_16x16x32_bf16 v[4:7], v[172:175], v[218:221], v[4:7]
	v_mfma_f32_16x16x32_bf16 v[0:3], v[180:183], v[218:221], v[0:3]
	s_barrier
	s_setprio 0
	s_add_i32 s38, 0, 0x18000
	s_add_i32 s39, 0, 0x1c000
	v_add_u32_e32 v156, s38, v169
	v_add_u32_e32 v180, s39, v169
	ds_read_b128 v[130:133], v156
	ds_read_b128 v[134:137], v156 offset:1024
	ds_read_b128 v[152:155], v156 offset:2048
	ds_read_b128 v[156:159], v156 offset:3072
	ds_read_b128 v[160:163], v180
	ds_read_b128 v[172:175], v180 offset:1024
	ds_read_b128 v[176:179], v180 offset:2048
	ds_read_b128 v[180:183], v180 offset:3072
	s_add_u32 s34, s86, 0x80000
	s_addc_u32 s35, s87, 0
	s_mov_b32 m0, s79
	ds_read_b128 v[184:187], v171 offset:32768
	ds_read_b128 v[188:191], v171 offset:33792
	ds_read_b128 v[192:195], v171 offset:34816
	ds_read_b128 v[196:199], v171 offset:35840
	ds_read_b128 v[202:205], v171 offset:36864
	ds_read_b128 v[210:213], v171 offset:37888
	ds_read_b128 v[214:217], v171 offset:38912
	ds_read_b128 v[218:221], v171 offset:39936
	global_load_lds_dwordx4 v146, s[34:35]
	s_mov_b32 m0, s90
	s_nop 0
	global_load_lds_dwordx4 v144, s[34:35]
	s_waitcnt vmcnt(8)
	s_waitcnt lgkmcnt(0)
	s_setprio 1
	s_barrier
	v_mfma_f32_16x16x32_bf16 v[126:129], v[130:133], v[184:187], v[126:129]
	v_mfma_f32_16x16x32_bf16 v[122:125], v[152:155], v[184:187], v[122:125]
	v_mfma_f32_16x16x32_bf16 v[110:113], v[130:133], v[192:195], v[110:113]
	v_mfma_f32_16x16x32_bf16 v[106:109], v[152:155], v[192:195], v[106:109]
	v_mfma_f32_16x16x32_bf16 v[92:95], v[130:133], v[202:205], v[92:95]
	v_mfma_f32_16x16x32_bf16 v[88:91], v[152:155], v[202:205], v[88:91]
	v_mfma_f32_16x16x32_bf16 v[76:79], v[130:133], v[214:217], v[76:79]
	v_mfma_f32_16x16x32_bf16 v[72:75], v[152:155], v[214:217], v[72:75]
	v_mfma_f32_16x16x32_bf16 v[126:129], v[134:137], v[188:191], v[126:129]
	v_mfma_f32_16x16x32_bf16 v[122:125], v[156:159], v[188:191], v[122:125]
	v_mfma_f32_16x16x32_bf16 v[110:113], v[134:137], v[196:199], v[110:113]
	v_mfma_f32_16x16x32_bf16 v[106:109], v[156:159], v[196:199], v[106:109]
	v_mfma_f32_16x16x32_bf16 v[92:95], v[134:137], v[210:213], v[92:95]
	v_mfma_f32_16x16x32_bf16 v[88:91], v[156:159], v[210:213], v[88:91]
	v_mfma_f32_16x16x32_bf16 v[76:79], v[134:137], v[218:221], v[76:79]
	v_mfma_f32_16x16x32_bf16 v[72:75], v[156:159], v[218:221], v[72:75]
	v_mfma_f32_16x16x32_bf16 v[118:121], v[160:163], v[184:187], v[118:121]
	v_mfma_f32_16x16x32_bf16 v[114:117], v[176:179], v[184:187], v[114:117]
	v_mfma_f32_16x16x32_bf16 v[102:105], v[160:163], v[192:195], v[102:105]
	v_mfma_f32_16x16x32_bf16 v[98:101], v[176:179], v[192:195], v[98:101]
	v_mfma_f32_16x16x32_bf16 v[84:87], v[160:163], v[202:205], v[84:87]
	v_mfma_f32_16x16x32_bf16 v[80:83], v[176:179], v[202:205], v[80:83]
	v_mfma_f32_16x16x32_bf16 v[68:71], v[160:163], v[214:217], v[68:71]
	v_mfma_f32_16x16x32_bf16 v[64:67], v[176:179], v[214:217], v[64:67]
	v_mfma_f32_16x16x32_bf16 v[118:121], v[172:175], v[188:191], v[118:121]
	v_mfma_f32_16x16x32_bf16 v[114:117], v[180:183], v[188:191], v[114:117]
	v_mfma_f32_16x16x32_bf16 v[102:105], v[172:175], v[196:199], v[102:105]
	v_mfma_f32_16x16x32_bf16 v[98:101], v[180:183], v[196:199], v[98:101]
	v_mfma_f32_16x16x32_bf16 v[84:87], v[172:175], v[210:213], v[84:87]
	v_mfma_f32_16x16x32_bf16 v[80:83], v[180:183], v[210:213], v[80:83]
	v_mfma_f32_16x16x32_bf16 v[68:71], v[172:175], v[218:221], v[68:71]
	v_mfma_f32_16x16x32_bf16 v[64:67], v[180:183], v[218:221], v[64:67]
	s_barrier
	s_setprio 0
	s_add_i32 s34, s38, s75
	s_mov_b32 m0, s34
	ds_read_b128 v[184:187], v171 offset:49152
	ds_read_b128 v[188:191], v171 offset:50176
	ds_read_b128 v[192:195], v171 offset:51200
	ds_read_b128 v[196:199], v171 offset:52224
	ds_read_b128 v[202:205], v171 offset:53248
	ds_read_b128 v[210:213], v171 offset:54272
	ds_read_b128 v[214:217], v171 offset:55296
	ds_read_b128 v[218:221], v171 offset:56320
	global_load_lds_dwordx4 v165, s[84:85]
	s_add_i32 m0, s34, 0x2000
	s_add_u32 s34, s84, 0x80080
	s_addc_u32 s35, s85, 0
	s_add_i32 s38, s39, s75
	global_load_lds_dwordx4 v223, s[84:85]
	s_mov_b32 m0, s38
	s_nop 0
	global_load_lds_dwordx4 v96, s[34:35]
	s_add_i32 m0, s38, 0x2000
	s_nop 0
	global_load_lds_dwordx4 v142, s[34:35]
	s_mov_b32 m0, s94
	s_nop 0
	global_load_lds_dwordx4 v225, s[86:87]
	s_mov_b32 m0, s95
	s_nop 0
	global_load_lds_dwordx4 v227, s[86:87]
	s_waitcnt vmcnt(8)
	s_waitcnt lgkmcnt(0)
	s_setprio 1
	s_barrier
	v_mfma_f32_16x16x32_bf16 v[60:63], v[130:133], v[184:187], v[60:63]
	v_mfma_f32_16x16x32_bf16 v[56:59], v[152:155], v[184:187], v[56:59]
	v_mfma_f32_16x16x32_bf16 v[44:47], v[130:133], v[192:195], v[44:47]
	v_mfma_f32_16x16x32_bf16 v[40:43], v[152:155], v[192:195], v[40:43]
	v_mfma_f32_16x16x32_bf16 v[28:31], v[130:133], v[202:205], v[28:31]
	v_mfma_f32_16x16x32_bf16 v[24:27], v[152:155], v[202:205], v[24:27]
	v_mfma_f32_16x16x32_bf16 v[12:15], v[130:133], v[214:217], v[12:15]
	v_mfma_f32_16x16x32_bf16 v[8:11], v[152:155], v[214:217], v[8:11]
	v_mfma_f32_16x16x32_bf16 v[60:63], v[134:137], v[188:191], v[60:63]
	v_mfma_f32_16x16x32_bf16 v[56:59], v[156:159], v[188:191], v[56:59]
	v_mfma_f32_16x16x32_bf16 v[44:47], v[134:137], v[196:199], v[44:47]
	v_mfma_f32_16x16x32_bf16 v[40:43], v[156:159], v[196:199], v[40:43]
	v_mfma_f32_16x16x32_bf16 v[28:31], v[134:137], v[210:213], v[28:31]
	v_mfma_f32_16x16x32_bf16 v[24:27], v[156:159], v[210:213], v[24:27]
	v_mfma_f32_16x16x32_bf16 v[12:15], v[134:137], v[218:221], v[12:15]
	v_mfma_f32_16x16x32_bf16 v[8:11], v[156:159], v[218:221], v[8:11]
	v_mfma_f32_16x16x32_bf16 v[52:55], v[160:163], v[184:187], v[52:55]
	v_mfma_f32_16x16x32_bf16 v[48:51], v[176:179], v[184:187], v[48:51]
	v_mfma_f32_16x16x32_bf16 v[36:39], v[160:163], v[192:195], v[36:39]
	v_mfma_f32_16x16x32_bf16 v[32:35], v[176:179], v[192:195], v[32:35]
	v_mfma_f32_16x16x32_bf16 v[20:23], v[160:163], v[202:205], v[20:23]
	v_mfma_f32_16x16x32_bf16 v[16:19], v[176:179], v[202:205], v[16:19]
	v_mfma_f32_16x16x32_bf16 v[4:7], v[160:163], v[214:217], v[4:7]
	v_mfma_f32_16x16x32_bf16 v[0:3], v[176:179], v[214:217], v[0:3]
	v_mfma_f32_16x16x32_bf16 v[52:55], v[172:175], v[188:191], v[52:55]
	v_mfma_f32_16x16x32_bf16 v[48:51], v[180:183], v[188:191], v[48:51]
	v_mfma_f32_16x16x32_bf16 v[36:39], v[172:175], v[196:199], v[36:39]
	v_mfma_f32_16x16x32_bf16 v[32:35], v[180:183], v[196:199], v[32:35]
	v_mfma_f32_16x16x32_bf16 v[20:23], v[172:175], v[210:213], v[20:23]
	v_mfma_f32_16x16x32_bf16 v[16:19], v[180:183], v[210:213], v[16:19]
	v_mfma_f32_16x16x32_bf16 v[4:7], v[172:175], v[218:221], v[4:7]
	v_mfma_f32_16x16x32_bf16 v[0:3], v[180:183], v[218:221], v[0:3]
	s_barrier
	s_setprio 0
	s_add_i32 s33, s33, 2
	s_add_u32 s44, s44, 0x100
	s_addc_u32 s45, s45, 0
	s_add_u32 s28, s28, 0x100
	s_addc_u32 s31, s31, 0
	s_cmp_gt_u32 s33, 29
	s_cbranch_scc0 .LBB0_1038
	v_mov_b32_e32 v243, 1
	v_readlane_b32 s0, v251, 54
	v_readlane_b32 s1, v251, 55
	s_and_b64 vcc, exec, s[0:1]
	s_cbranch_vccz .LBB0_1041
	s_barrier

.LBB0_1265:
	s_add_u32 s35, s42, 0xffe00080
	s_addc_u32 s44, s43, -1
	s_add_i32 s54, 0, 0x10000
	s_cmpk_eq_i32 s33, 0x7c
	s_cselect_b32 s53, s12, s44
	s_cselect_b32 s52, s17, s35
	v_add_u32_e32 v148, s54, v153
	s_cselect_b32 s45, s5, s28
	s_cselect_b32 s44, s18, s20
	s_add_i32 s35, 0, 0x14000
	ds_read_b128 v[144:147], v148
	ds_read_b128 v[154:157], v148 offset:1024
	ds_read_b128 v[160:163], v148 offset:2048
	ds_read_b128 v[164:167], v148 offset:3072
	v_add_u32_e32 v148, s35, v153
	ds_read_b128 v[168:171], v148
	ds_read_b128 v[172:175], v148 offset:1024
	ds_read_b128 v[176:179], v148 offset:2048
	ds_read_b128 v[180:183], v148 offset:3072
	s_add_i32 m0, s59, 0xc000
	ds_read_b128 v[184:187], v159
	ds_read_b128 v[188:191], v159 offset:1024
	ds_read_b128 v[192:195], v159 offset:2048
	ds_read_b128 v[196:199], v159 offset:3072
	ds_read_b128 v[202:205], v159 offset:4096
	ds_read_b128 v[210:213], v159 offset:5120
	ds_read_b128 v[214:217], v159 offset:6144
	ds_read_b128 v[218:221], v159 offset:7168
	global_load_lds_dwordx4 v140, s[42:43]
	s_add_i32 m0, s59, 0xe000
	s_nop 0
	global_load_lds_dwordx4 v142, s[42:43]
	s_waitcnt vmcnt(8)
	s_waitcnt lgkmcnt(0)
	s_setprio 1
	s_barrier
	v_mfma_f32_16x16x32_bf16 v[126:129], v[144:147], v[184:187], v[126:129]
	v_mfma_f32_16x16x32_bf16 v[122:125], v[160:163], v[184:187], v[122:125]
	v_mfma_f32_16x16x32_bf16 v[110:113], v[144:147], v[192:195], v[110:113]
	v_mfma_f32_16x16x32_bf16 v[106:109], v[160:163], v[192:195], v[106:109]
	v_mfma_f32_16x16x32_bf16 v[92:95], v[144:147], v[202:205], v[92:95]
	v_mfma_f32_16x16x32_bf16 v[88:91], v[160:163], v[202:205], v[88:91]
	v_mfma_f32_16x16x32_bf16 v[76:79], v[144:147], v[214:217], v[76:79]
	v_mfma_f32_16x16x32_bf16 v[72:75], v[160:163], v[214:217], v[72:75]
	v_mfma_f32_16x16x32_bf16 v[126:129], v[154:157], v[188:191], v[126:129]
	v_mfma_f32_16x16x32_bf16 v[122:125], v[164:167], v[188:191], v[122:125]
	v_mfma_f32_16x16x32_bf16 v[110:113], v[154:157], v[196:199], v[110:113]
	v_mfma_f32_16x16x32_bf16 v[106:109], v[164:167], v[196:199], v[106:109]
	v_mfma_f32_16x16x32_bf16 v[92:95], v[154:157], v[210:213], v[92:95]
	v_mfma_f32_16x16x32_bf16 v[88:91], v[164:167], v[210:213], v[88:91]
	v_mfma_f32_16x16x32_bf16 v[76:79], v[154:157], v[218:221], v[76:79]
	v_mfma_f32_16x16x32_bf16 v[72:75], v[164:167], v[218:221], v[72:75]
	v_mfma_f32_16x16x32_bf16 v[118:121], v[168:171], v[184:187], v[118:121]
	v_mfma_f32_16x16x32_bf16 v[114:117], v[176:179], v[184:187], v[114:117]
	v_mfma_f32_16x16x32_bf16 v[102:105], v[168:171], v[192:195], v[102:105]
	v_mfma_f32_16x16x32_bf16 v[98:101], v[176:179], v[192:195], v[98:101]
	v_mfma_f32_16x16x32_bf16 v[84:87], v[168:171], v[202:205], v[84:87]
	v_mfma_f32_16x16x32_bf16 v[80:83], v[176:179], v[202:205], v[80:83]
	v_mfma_f32_16x16x32_bf16 v[68:71], v[168:171], v[214:217], v[68:71]
	v_mfma_f32_16x16x32_bf16 v[64:67], v[176:179], v[214:217], v[64:67]
	v_mfma_f32_16x16x32_bf16 v[118:121], v[172:175], v[188:191], v[118:121]
	v_mfma_f32_16x16x32_bf16 v[114:117], v[180:183], v[188:191], v[114:117]
	v_mfma_f32_16x16x32_bf16 v[102:105], v[172:175], v[196:199], v[102:105]
	v_mfma_f32_16x16x32_bf16 v[98:101], v[180:183], v[196:199], v[98:101]
	v_mfma_f32_16x16x32_bf16 v[84:87], v[172:175], v[210:213], v[84:87]
	v_mfma_f32_16x16x32_bf16 v[80:83], v[180:183], v[210:213], v[80:83]
	v_mfma_f32_16x16x32_bf16 v[68:71], v[172:175], v[218:221], v[68:71]
	v_mfma_f32_16x16x32_bf16 v[64:67], v[180:183], v[218:221], v[64:67]
	s_barrier
	s_setprio 0
	s_add_i32 s54, s54, s75
	s_mov_b32 m0, s54
	ds_read_b128 v[184:187], v159 offset:16384
	ds_read_b128 v[188:191], v159 offset:17408
	ds_read_b128 v[192:195], v159 offset:18432
	ds_read_b128 v[196:199], v159 offset:19456
	ds_read_b128 v[202:205], v159 offset:20480
	ds_read_b128 v[210:213], v159 offset:21504
	ds_read_b128 v[214:217], v159 offset:22528
	ds_read_b128 v[218:221], v159 offset:23552
	global_load_lds_dwordx4 v96, s[44:45]
	s_add_i32 m0, s54, 0x2000
	s_add_u32 s54, s44, 0x200000
	s_addc_u32 s55, s45, 0
	s_add_i32 s35, s35, s75
	global_load_lds_dwordx4 v134, s[44:45]
	s_mov_b32 m0, s35
	s_nop 0
	global_load_lds_dwordx4 v96, s[54:55]
	s_add_i32 m0, s35, 0x2000
	s_nop 0
	global_load_lds_dwordx4 v134, s[54:55]
	s_mov_b32 m0, s59
	s_nop 0
	global_load_lds_dwordx4 v138, s[52:53]
	s_mov_b32 m0, s68
	s_nop 0
	global_load_lds_dwordx4 v136, s[52:53]
	s_waitcnt vmcnt(8)
	v_mov_b32_e32 v243, 0
	s_waitcnt lgkmcnt(0)
	s_setprio 1
	s_barrier
	v_mfma_f32_16x16x32_bf16 v[60:63], v[144:147], v[184:187], v[60:63]
	v_mfma_f32_16x16x32_bf16 v[56:59], v[160:163], v[184:187], v[56:59]
	v_mfma_f32_16x16x32_bf16 v[44:47], v[144:147], v[192:195], v[44:47]
	v_mfma_f32_16x16x32_bf16 v[40:43], v[160:163], v[192:195], v[40:43]
	v_mfma_f32_16x16x32_bf16 v[28:31], v[144:147], v[202:205], v[28:31]
	v_mfma_f32_16x16x32_bf16 v[24:27], v[160:163], v[202:205], v[24:27]
	v_mfma_f32_16x16x32_bf16 v[12:15], v[144:147], v[214:217], v[12:15]
	v_mfma_f32_16x16x32_bf16 v[8:11], v[160:163], v[214:217], v[8:11]
	v_mfma_f32_16x16x32_bf16 v[60:63], v[154:157], v[188:191], v[60:63]
	v_mfma_f32_16x16x32_bf16 v[56:59], v[164:167], v[188:191], v[56:59]
	v_mfma_f32_16x16x32_bf16 v[44:47], v[154:157], v[196:199], v[44:47]
	v_mfma_f32_16x16x32_bf16 v[40:43], v[164:167], v[196:199], v[40:43]
	v_mfma_f32_16x16x32_bf16 v[28:31], v[154:157], v[210:213], v[28:31]
	v_mfma_f32_16x16x32_bf16 v[24:27], v[164:167], v[210:213], v[24:27]
	v_mfma_f32_16x16x32_bf16 v[12:15], v[154:157], v[218:221], v[12:15]
	v_mfma_f32_16x16x32_bf16 v[8:11], v[164:167], v[218:221], v[8:11]
	v_mfma_f32_16x16x32_bf16 v[52:55], v[168:171], v[184:187], v[52:55]
	v_mfma_f32_16x16x32_bf16 v[48:51], v[176:179], v[184:187], v[48:51]
	v_mfma_f32_16x16x32_bf16 v[36:39], v[168:171], v[192:195], v[36:39]
	v_mfma_f32_16x16x32_bf16 v[32:35], v[176:179], v[192:195], v[32:35]
	v_mfma_f32_16x16x32_bf16 v[20:23], v[168:171], v[202:205], v[20:23]
	v_mfma_f32_16x16x32_bf16 v[16:19], v[176:179], v[202:205], v[16:19]
	v_mfma_f32_16x16x32_bf16 v[4:7], v[168:171], v[214:217], v[4:7]
	v_mfma_f32_16x16x32_bf16 v[0:3], v[176:179], v[214:217], v[0:3]
	v_mfma_f32_16x16x32_bf16 v[52:55], v[172:175], v[188:191], v[52:55]
	v_mfma_f32_16x16x32_bf16 v[48:51], v[180:183], v[188:191], v[48:51]
	v_mfma_f32_16x16x32_bf16 v[36:39], v[172:175], v[196:199], v[36:39]
	v_mfma_f32_16x16x32_bf16 v[32:35], v[180:183], v[196:199], v[32:35]
	v_mfma_f32_16x16x32_bf16 v[20:23], v[172:175], v[210:213], v[20:23]
	v_mfma_f32_16x16x32_bf16 v[16:19], v[180:183], v[210:213], v[16:19]
	v_mfma_f32_16x16x32_bf16 v[4:7], v[172:175], v[218:221], v[4:7]
	v_mfma_f32_16x16x32_bf16 v[0:3], v[180:183], v[218:221], v[0:3]
	s_barrier
	s_setprio 0
	s_add_i32 s35, 0, 0x18000
	s_add_i32 s54, 0, 0x1c000
	v_add_u32_e32 v164, s35, v153
	v_add_u32_e32 v180, s54, v153
	ds_read_b128 v[144:147], v164
	ds_read_b128 v[154:157], v164 offset:1024
	ds_read_b128 v[160:163], v164 offset:2048
	ds_read_b128 v[164:167], v164 offset:3072
	ds_read_b128 v[168:171], v180
	ds_read_b128 v[172:175], v180 offset:1024
	ds_read_b128 v[176:179], v180 offset:2048
	ds_read_b128 v[180:183], v180 offset:3072
	s_mov_b32 m0, s69
	ds_read_b128 v[184:187], v159 offset:32768
	ds_read_b128 v[188:191], v159 offset:33792
	ds_read_b128 v[192:195], v159 offset:34816
	ds_read_b128 v[196:199], v159 offset:35840
	ds_read_b128 v[202:205], v159 offset:36864
	ds_read_b128 v[210:213], v159 offset:37888
	ds_read_b128 v[214:217], v159 offset:38912
	ds_read_b128 v[218:221], v159 offset:39936
	global_load_lds_dwordx4 v226, s[52:53]
	s_mov_b32 m0, s79
	s_nop 0
	global_load_lds_dwordx4 v227, s[52:53]
	s_waitcnt vmcnt(8)
	s_waitcnt lgkmcnt(0)
	s_setprio 1
	s_barrier
	v_mfma_f32_16x16x32_bf16 v[126:129], v[144:147], v[184:187], v[126:129]
	v_mfma_f32_16x16x32_bf16 v[122:125], v[160:163], v[184:187], v[122:125]
	v_mfma_f32_16x16x32_bf16 v[110:113], v[144:147], v[192:195], v[110:113]
	v_mfma_f32_16x16x32_bf16 v[106:109], v[160:163], v[192:195], v[106:109]
	v_mfma_f32_16x16x32_bf16 v[92:95], v[144:147], v[202:205], v[92:95]
	v_mfma_f32_16x16x32_bf16 v[88:91], v[160:163], v[202:205], v[88:91]
	v_mfma_f32_16x16x32_bf16 v[76:79], v[144:147], v[214:217], v[76:79]
	v_mfma_f32_16x16x32_bf16 v[72:75], v[160:163], v[214:217], v[72:75]
	v_mfma_f32_16x16x32_bf16 v[126:129], v[154:157], v[188:191], v[126:129]
	v_mfma_f32_16x16x32_bf16 v[122:125], v[164:167], v[188:191], v[122:125]
	v_mfma_f32_16x16x32_bf16 v[110:113], v[154:157], v[196:199], v[110:113]
	v_mfma_f32_16x16x32_bf16 v[106:109], v[164:167], v[196:199], v[106:109]
	v_mfma_f32_16x16x32_bf16 v[92:95], v[154:157], v[210:213], v[92:95]
	v_mfma_f32_16x16x32_bf16 v[88:91], v[164:167], v[210:213], v[88:91]
	v_mfma_f32_16x16x32_bf16 v[76:79], v[154:157], v[218:221], v[76:79]
	v_mfma_f32_16x16x32_bf16 v[72:75], v[164:167], v[218:221], v[72:75]
	v_mfma_f32_16x16x32_bf16 v[118:121], v[168:171], v[184:187], v[118:121]
	v_mfma_f32_16x16x32_bf16 v[114:117], v[176:179], v[184:187], v[114:117]
	v_mfma_f32_16x16x32_bf16 v[102:105], v[168:171], v[192:195], v[102:105]
	v_mfma_f32_16x16x32_bf16 v[98:101], v[176:179], v[192:195], v[98:101]
	v_mfma_f32_16x16x32_bf16 v[84:87], v[168:171], v[202:205], v[84:87]
	v_mfma_f32_16x16x32_bf16 v[80:83], v[176:179], v[202:205], v[80:83]
	v_mfma_f32_16x16x32_bf16 v[68:71], v[168:171], v[214:217], v[68:71]
	v_mfma_f32_16x16x32_bf16 v[64:67], v[176:179], v[214:217], v[64:67]
	v_mfma_f32_16x16x32_bf16 v[118:121], v[172:175], v[188:191], v[118:121]
	v_mfma_f32_16x16x32_bf16 v[114:117], v[180:183], v[188:191], v[114:117]
	v_mfma_f32_16x16x32_bf16 v[102:105], v[172:175], v[196:199], v[102:105]
	v_mfma_f32_16x16x32_bf16 v[98:101], v[180:183], v[196:199], v[98:101]
	v_mfma_f32_16x16x32_bf16 v[84:87], v[172:175], v[210:213], v[84:87]
	v_mfma_f32_16x16x32_bf16 v[80:83], v[180:183], v[210:213], v[80:83]
	v_mfma_f32_16x16x32_bf16 v[68:71], v[172:175], v[218:221], v[68:71]
	v_mfma_f32_16x16x32_bf16 v[64:67], v[180:183], v[218:221], v[64:67]
	s_barrier
	s_setprio 0
	s_add_i32 s35, s35, s75
	s_mov_b32 m0, s35
	ds_read_b128 v[184:187], v159 offset:49152
	ds_read_b128 v[188:191], v159 offset:50176
	ds_read_b128 v[192:195], v159 offset:51200
	ds_read_b128 v[196:199], v159 offset:52224
	ds_read_b128 v[202:205], v159 offset:53248
	ds_read_b128 v[210:213], v159 offset:54272
	ds_read_b128 v[214:217], v159 offset:55296
	ds_read_b128 v[218:221], v159 offset:56320
	global_load_lds_dwordx4 v222, s[44:45]
	s_add_i32 m0, s35, 0x2000
	s_add_i32 s35, s54, s75
	global_load_lds_dwordx4 v223, s[44:45]
	s_add_u32 s44, s44, 0x200080
	s_addc_u32 s45, s45, 0
	s_mov_b32 m0, s35
	s_nop 0
	global_load_lds_dwordx4 v96, s[44:45]
	s_add_i32 m0, s35, 0x2000
	s_nop 0
	global_load_lds_dwordx4 v134, s[44:45]
	s_mov_b32 m0, s10
	s_nop 0
	global_load_lds_dwordx4 v224, s[52:53]
	s_mov_b32 m0, s77
	s_nop 0
	global_load_lds_dwordx4 v225, s[52:53]
	s_waitcnt vmcnt(8)
	s_waitcnt lgkmcnt(0)
	s_setprio 1
	s_barrier
	v_mfma_f32_16x16x32_bf16 v[60:63], v[144:147], v[184:187], v[60:63]
	v_mfma_f32_16x16x32_bf16 v[56:59], v[160:163], v[184:187], v[56:59]
	v_mfma_f32_16x16x32_bf16 v[44:47], v[144:147], v[192:195], v[44:47]
	v_mfma_f32_16x16x32_bf16 v[40:43], v[160:163], v[192:195], v[40:43]
	v_mfma_f32_16x16x32_bf16 v[28:31], v[144:147], v[202:205], v[28:31]
	v_mfma_f32_16x16x32_bf16 v[24:27], v[160:163], v[202:205], v[24:27]
	v_mfma_f32_16x16x32_bf16 v[12:15], v[144:147], v[214:217], v[12:15]
	v_mfma_f32_16x16x32_bf16 v[8:11], v[160:163], v[214:217], v[8:11]
	v_mfma_f32_16x16x32_bf16 v[60:63], v[154:157], v[188:191], v[60:63]
	v_mfma_f32_16x16x32_bf16 v[56:59], v[164:167], v[188:191], v[56:59]
	v_mfma_f32_16x16x32_bf16 v[44:47], v[154:157], v[196:199], v[44:47]
	v_mfma_f32_16x16x32_bf16 v[40:43], v[164:167], v[196:199], v[40:43]
	v_mfma_f32_16x16x32_bf16 v[28:31], v[154:157], v[210:213], v[28:31]
	v_mfma_f32_16x16x32_bf16 v[24:27], v[164:167], v[210:213], v[24:27]
	v_mfma_f32_16x16x32_bf16 v[12:15], v[154:157], v[218:221], v[12:15]
	v_mfma_f32_16x16x32_bf16 v[8:11], v[164:167], v[218:221], v[8:11]
	v_mfma_f32_16x16x32_bf16 v[52:55], v[168:171], v[184:187], v[52:55]
	v_mfma_f32_16x16x32_bf16 v[48:51], v[176:179], v[184:187], v[48:51]
	v_mfma_f32_16x16x32_bf16 v[36:39], v[168:171], v[192:195], v[36:39]
	v_mfma_f32_16x16x32_bf16 v[32:35], v[176:179], v[192:195], v[32:35]
	v_mfma_f32_16x16x32_bf16 v[20:23], v[168:171], v[202:205], v[20:23]
	v_mfma_f32_16x16x32_bf16 v[16:19], v[176:179], v[202:205], v[16:19]
	v_mfma_f32_16x16x32_bf16 v[4:7], v[168:171], v[214:217], v[4:7]
	v_mfma_f32_16x16x32_bf16 v[0:3], v[176:179], v[214:217], v[0:3]
	v_mfma_f32_16x16x32_bf16 v[52:55], v[172:175], v[188:191], v[52:55]
	v_mfma_f32_16x16x32_bf16 v[48:51], v[180:183], v[188:191], v[48:51]
	v_mfma_f32_16x16x32_bf16 v[36:39], v[172:175], v[196:199], v[36:39]
	v_mfma_f32_16x16x32_bf16 v[32:35], v[180:183], v[196:199], v[32:35]
	v_mfma_f32_16x16x32_bf16 v[20:23], v[172:175], v[210:213], v[20:23]
	v_mfma_f32_16x16x32_bf16 v[16:19], v[180:183], v[210:213], v[16:19]
	v_mfma_f32_16x16x32_bf16 v[4:7], v[172:175], v[218:221], v[4:7]
	v_mfma_f32_16x16x32_bf16 v[0:3], v[180:183], v[218:221], v[0:3]
	s_barrier
	s_setprio 0
	s_add_i32 s33, s33, 2
	s_add_u32 s42, s42, 0x100
	s_addc_u32 s43, s43, 0
	s_add_u32 s20, s20, 0x100
	s_addc_u32 s28, s28, 0
	s_cmpk_gt_u32 s33, 0x7d
	s_cbranch_scc0 .LBB0_1265
	v_mov_b32_e32 v243, 1
	v_readlane_b32 s6, v251, 54
	v_readlane_b32 s7, v251, 55
	s_and_b64 vcc, exec, s[6:7]
	s_movk_i32 s53, 0x6000
	s_cbranch_vccz .LBB0_1268
	s_barrier

.LBB0_1284:
	s_add_u32 s33, s52, 0xfff80080
	s_addc_u32 s38, s53, -1
	s_add_i32 s39, 0, 0x10000
	s_cmp_eq_u32 s28, 28
	s_cselect_b32 s83, s3, s38
	s_cselect_b32 s82, s12, s33
	v_add_u32_e32 v144, s39, v150
	s_cselect_b32 s69, s17, s25
	s_cselect_b32 s68, s18, s20
	s_add_i32 s33, 0, 0x14000
	ds_read_b128 v[154:157], v144
	ds_read_b128 v[158:161], v144 offset:1024
	ds_read_b128 v[162:165], v144 offset:2048
	ds_read_b128 v[166:169], v144 offset:3072
	v_add_u32_e32 v144, s33, v150
	ds_read_b128 v[170:173], v144
	ds_read_b128 v[174:177], v144 offset:1024
	ds_read_b128 v[178:181], v144 offset:2048
	ds_read_b128 v[182:185], v144 offset:3072
	s_add_i32 m0, s34, 0xc000
	ds_read_b128 v[186:189], v152
	ds_read_b128 v[190:193], v152 offset:1024
	ds_read_b128 v[194:197], v152 offset:2048
	ds_read_b128 v[202:205], v152 offset:3072
	ds_read_b128 v[210:213], v152 offset:4096
	ds_read_b128 v[214:217], v152 offset:5120
	ds_read_b128 v[218:221], v152 offset:6144
	ds_read_b128 v[222:225], v152 offset:7168
	global_load_lds_dwordx4 v140, s[52:53]
	s_add_i32 m0, s34, 0xe000
	s_nop 0
	global_load_lds_dwordx4 v142, s[52:53]
	s_waitcnt vmcnt(8)
	s_waitcnt lgkmcnt(0)
	s_setprio 1
	s_barrier
	v_mfma_f32_16x16x32_bf16 v[126:129], v[154:157], v[186:189], v[126:129]
	v_mfma_f32_16x16x32_bf16 v[122:125], v[162:165], v[186:189], v[122:125]
	v_mfma_f32_16x16x32_bf16 v[110:113], v[154:157], v[194:197], v[110:113]
	v_mfma_f32_16x16x32_bf16 v[106:109], v[162:165], v[194:197], v[106:109]
	v_mfma_f32_16x16x32_bf16 v[92:95], v[154:157], v[210:213], v[92:95]
	v_mfma_f32_16x16x32_bf16 v[88:91], v[162:165], v[210:213], v[88:91]
	v_mfma_f32_16x16x32_bf16 v[76:79], v[154:157], v[218:221], v[76:79]
	v_mfma_f32_16x16x32_bf16 v[72:75], v[162:165], v[218:221], v[72:75]
	v_mfma_f32_16x16x32_bf16 v[126:129], v[158:161], v[190:193], v[126:129]
	v_mfma_f32_16x16x32_bf16 v[122:125], v[166:169], v[190:193], v[122:125]
	v_mfma_f32_16x16x32_bf16 v[110:113], v[158:161], v[202:205], v[110:113]
	v_mfma_f32_16x16x32_bf16 v[106:109], v[166:169], v[202:205], v[106:109]
	v_mfma_f32_16x16x32_bf16 v[92:95], v[158:161], v[214:217], v[92:95]
	v_mfma_f32_16x16x32_bf16 v[88:91], v[166:169], v[214:217], v[88:91]
	v_mfma_f32_16x16x32_bf16 v[76:79], v[158:161], v[222:225], v[76:79]
	v_mfma_f32_16x16x32_bf16 v[72:75], v[166:169], v[222:225], v[72:75]
	v_mfma_f32_16x16x32_bf16 v[118:121], v[170:173], v[186:189], v[118:121]
	v_mfma_f32_16x16x32_bf16 v[114:117], v[178:181], v[186:189], v[114:117]
	v_mfma_f32_16x16x32_bf16 v[102:105], v[170:173], v[194:197], v[102:105]
	v_mfma_f32_16x16x32_bf16 v[98:101], v[178:181], v[194:197], v[98:101]
	v_mfma_f32_16x16x32_bf16 v[84:87], v[170:173], v[210:213], v[84:87]
	v_mfma_f32_16x16x32_bf16 v[80:83], v[178:181], v[210:213], v[80:83]
	v_mfma_f32_16x16x32_bf16 v[68:71], v[170:173], v[218:221], v[68:71]
	v_mfma_f32_16x16x32_bf16 v[64:67], v[178:181], v[218:221], v[64:67]
	v_mfma_f32_16x16x32_bf16 v[118:121], v[174:177], v[190:193], v[118:121]
	v_mfma_f32_16x16x32_bf16 v[114:117], v[182:185], v[190:193], v[114:117]
	v_mfma_f32_16x16x32_bf16 v[102:105], v[174:177], v[202:205], v[102:105]
	v_mfma_f32_16x16x32_bf16 v[98:101], v[182:185], v[202:205], v[98:101]
	v_mfma_f32_16x16x32_bf16 v[84:87], v[174:177], v[214:217], v[84:87]
	v_mfma_f32_16x16x32_bf16 v[80:83], v[182:185], v[214:217], v[80:83]
	v_mfma_f32_16x16x32_bf16 v[68:71], v[174:177], v[222:225], v[68:71]
	v_mfma_f32_16x16x32_bf16 v[64:67], v[182:185], v[222:225], v[64:67]
	s_barrier
	s_setprio 0
	s_add_i32 s38, s39, s75
	s_mov_b32 m0, s38
	ds_read_b128 v[186:189], v152 offset:16384
	ds_read_b128 v[190:193], v152 offset:17408
	ds_read_b128 v[194:197], v152 offset:18432
	ds_read_b128 v[202:205], v152 offset:19456
	ds_read_b128 v[210:213], v152 offset:20480
	ds_read_b128 v[214:217], v152 offset:21504
	ds_read_b128 v[218:221], v152 offset:22528
	ds_read_b128 v[222:225], v152 offset:23552
	global_load_lds_dwordx4 v96, s[68:69]
	s_add_i32 m0, s38, 0x2000
	s_add_u32 s38, s68, 0x80000
	s_addc_u32 s39, s69, 0
	s_add_i32 s33, s33, s75
	global_load_lds_dwordx4 v134, s[68:69]
	s_mov_b32 m0, s33
	s_nop 0
	global_load_lds_dwordx4 v96, s[38:39]
	s_add_i32 m0, s33, 0x2000
	s_nop 0
	global_load_lds_dwordx4 v134, s[38:39]
	s_mov_b32 m0, s34
	s_nop 0
	global_load_lds_dwordx4 v138, s[82:83]
	s_mov_b32 m0, s35
	s_nop 0
	global_load_lds_dwordx4 v136, s[82:83]
	s_waitcnt vmcnt(8)
	v_mov_b32_e32 v243, 0
	s_waitcnt lgkmcnt(0)
	s_setprio 1
	s_barrier
	v_mfma_f32_16x16x32_bf16 v[60:63], v[154:157], v[186:189], v[60:63]
	v_mfma_f32_16x16x32_bf16 v[56:59], v[162:165], v[186:189], v[56:59]
	v_mfma_f32_16x16x32_bf16 v[44:47], v[154:157], v[194:197], v[44:47]
	v_mfma_f32_16x16x32_bf16 v[40:43], v[162:165], v[194:197], v[40:43]
	v_mfma_f32_16x16x32_bf16 v[28:31], v[154:157], v[210:213], v[28:31]
	v_mfma_f32_16x16x32_bf16 v[24:27], v[162:165], v[210:213], v[24:27]
	v_mfma_f32_16x16x32_bf16 v[12:15], v[154:157], v[218:221], v[12:15]
	v_mfma_f32_16x16x32_bf16 v[8:11], v[162:165], v[218:221], v[8:11]
	v_mfma_f32_16x16x32_bf16 v[60:63], v[158:161], v[190:193], v[60:63]
	v_mfma_f32_16x16x32_bf16 v[56:59], v[166:169], v[190:193], v[56:59]
	v_mfma_f32_16x16x32_bf16 v[44:47], v[158:161], v[202:205], v[44:47]
	v_mfma_f32_16x16x32_bf16 v[40:43], v[166:169], v[202:205], v[40:43]
	v_mfma_f32_16x16x32_bf16 v[28:31], v[158:161], v[214:217], v[28:31]
	v_mfma_f32_16x16x32_bf16 v[24:27], v[166:169], v[214:217], v[24:27]
	v_mfma_f32_16x16x32_bf16 v[12:15], v[158:161], v[222:225], v[12:15]
	v_mfma_f32_16x16x32_bf16 v[8:11], v[166:169], v[222:225], v[8:11]
	v_mfma_f32_16x16x32_bf16 v[52:55], v[170:173], v[186:189], v[52:55]
	v_mfma_f32_16x16x32_bf16 v[48:51], v[178:181], v[186:189], v[48:51]
	v_mfma_f32_16x16x32_bf16 v[36:39], v[170:173], v[194:197], v[36:39]
	v_mfma_f32_16x16x32_bf16 v[32:35], v[178:181], v[194:197], v[32:35]
	v_mfma_f32_16x16x32_bf16 v[20:23], v[170:173], v[210:213], v[20:23]
	v_mfma_f32_16x16x32_bf16 v[16:19], v[178:181], v[210:213], v[16:19]
	v_mfma_f32_16x16x32_bf16 v[4:7], v[170:173], v[218:221], v[4:7]
	v_mfma_f32_16x16x32_bf16 v[0:3], v[178:181], v[218:221], v[0:3]
	v_mfma_f32_16x16x32_bf16 v[52:55], v[174:177], v[190:193], v[52:55]
	v_mfma_f32_16x16x32_bf16 v[48:51], v[182:185], v[190:193], v[48:51]
	v_mfma_f32_16x16x32_bf16 v[36:39], v[174:177], v[202:205], v[36:39]
	v_mfma_f32_16x16x32_bf16 v[32:35], v[182:185], v[202:205], v[32:35]
	v_mfma_f32_16x16x32_bf16 v[20:23], v[174:177], v[214:217], v[20:23]
	v_mfma_f32_16x16x32_bf16 v[16:19], v[182:185], v[214:217], v[16:19]
	v_mfma_f32_16x16x32_bf16 v[4:7], v[174:177], v[222:225], v[4:7]
	v_mfma_f32_16x16x32_bf16 v[0:3], v[182:185], v[222:225], v[0:3]
	s_barrier
	s_setprio 0
	s_add_i32 s33, 0, 0x18000
	v_add_u32_e32 v153, s33, v150
	s_add_i32 s54, 0, 0x1c000
	ds_read_b128 v[154:157], v153
	ds_read_b128 v[158:161], v153 offset:1024
	ds_read_b128 v[162:165], v153 offset:2048
	ds_read_b128 v[166:169], v153 offset:3072
	v_add_u32_e32 v153, s54, v150
	ds_read_b128 v[170:173], v153
	ds_read_b128 v[174:177], v153 offset:1024
	ds_read_b128 v[178:181], v153 offset:2048
	ds_read_b128 v[182:185], v153 offset:3072
	s_add_u32 s38, s82, 0x80000
	s_addc_u32 s39, s83, 0
	s_mov_b32 m0, s50
	ds_read_b128 v[186:189], v152 offset:32768
	ds_read_b128 v[190:193], v152 offset:33792
	ds_read_b128 v[194:197], v152 offset:34816
	ds_read_b128 v[202:205], v152 offset:35840
	ds_read_b128 v[210:213], v152 offset:36864
	ds_read_b128 v[214:217], v152 offset:37888
	ds_read_b128 v[218:221], v152 offset:38912
	ds_read_b128 v[222:225], v152 offset:39936
	global_load_lds_dwordx4 v138, s[38:39]
	s_mov_b32 m0, s51
	s_nop 0
	global_load_lds_dwordx4 v136, s[38:39]
	s_waitcnt vmcnt(8)
	s_waitcnt lgkmcnt(0)
	s_setprio 1
	s_barrier
	v_mfma_f32_16x16x32_bf16 v[126:129], v[154:157], v[186:189], v[126:129]
	v_mfma_f32_16x16x32_bf16 v[122:125], v[162:165], v[186:189], v[122:125]
	v_mfma_f32_16x16x32_bf16 v[110:113], v[154:157], v[194:197], v[110:113]
	v_mfma_f32_16x16x32_bf16 v[106:109], v[162:165], v[194:197], v[106:109]
	v_mfma_f32_16x16x32_bf16 v[92:95], v[154:157], v[210:213], v[92:95]
	v_mfma_f32_16x16x32_bf16 v[88:91], v[162:165], v[210:213], v[88:91]
	v_mfma_f32_16x16x32_bf16 v[76:79], v[154:157], v[218:221], v[76:79]
	v_mfma_f32_16x16x32_bf16 v[72:75], v[162:165], v[218:221], v[72:75]
	v_mfma_f32_16x16x32_bf16 v[126:129], v[158:161], v[190:193], v[126:129]
	v_mfma_f32_16x16x32_bf16 v[122:125], v[166:169], v[190:193], v[122:125]
	v_mfma_f32_16x16x32_bf16 v[110:113], v[158:161], v[202:205], v[110:113]
	v_mfma_f32_16x16x32_bf16 v[106:109], v[166:169], v[202:205], v[106:109]
	v_mfma_f32_16x16x32_bf16 v[92:95], v[158:161], v[214:217], v[92:95]
	v_mfma_f32_16x16x32_bf16 v[88:91], v[166:169], v[214:217], v[88:91]
	v_mfma_f32_16x16x32_bf16 v[76:79], v[158:161], v[222:225], v[76:79]
	v_mfma_f32_16x16x32_bf16 v[72:75], v[166:169], v[222:225], v[72:75]
	v_mfma_f32_16x16x32_bf16 v[118:121], v[170:173], v[186:189], v[118:121]
	v_mfma_f32_16x16x32_bf16 v[114:117], v[178:181], v[186:189], v[114:117]
	v_mfma_f32_16x16x32_bf16 v[102:105], v[170:173], v[194:197], v[102:105]
	v_mfma_f32_16x16x32_bf16 v[98:101], v[178:181], v[194:197], v[98:101]
	v_mfma_f32_16x16x32_bf16 v[84:87], v[170:173], v[210:213], v[84:87]
	v_mfma_f32_16x16x32_bf16 v[80:83], v[178:181], v[210:213], v[80:83]
	v_mfma_f32_16x16x32_bf16 v[68:71], v[170:173], v[218:221], v[68:71]
	v_mfma_f32_16x16x32_bf16 v[64:67], v[178:181], v[218:221], v[64:67]
	v_mfma_f32_16x16x32_bf16 v[118:121], v[174:177], v[190:193], v[118:121]
	v_mfma_f32_16x16x32_bf16 v[114:117], v[182:185], v[190:193], v[114:117]
	v_mfma_f32_16x16x32_bf16 v[102:105], v[174:177], v[202:205], v[102:105]
	v_mfma_f32_16x16x32_bf16 v[98:101], v[182:185], v[202:205], v[98:101]
	v_mfma_f32_16x16x32_bf16 v[84:87], v[174:177], v[214:217], v[84:87]
	v_mfma_f32_16x16x32_bf16 v[80:83], v[182:185], v[214:217], v[80:83]
	v_mfma_f32_16x16x32_bf16 v[68:71], v[174:177], v[222:225], v[68:71]
	v_mfma_f32_16x16x32_bf16 v[64:67], v[182:185], v[222:225], v[64:67]
	s_barrier
	s_setprio 0
	s_add_i32 s33, s33, s75
	s_mov_b32 m0, s33
	ds_read_b128 v[186:189], v152 offset:49152
	ds_read_b128 v[190:193], v152 offset:50176
	ds_read_b128 v[194:197], v152 offset:51200
	ds_read_b128 v[202:205], v152 offset:52224
	ds_read_b128 v[210:213], v152 offset:53248
	ds_read_b128 v[214:217], v152 offset:54272
	ds_read_b128 v[218:221], v152 offset:55296
	ds_read_b128 v[222:225], v152 offset:56320
	global_load_lds_dwordx4 v145, s[68:69]
	s_add_i32 m0, s33, 0x2000
	s_add_u32 s38, s68, 0x80080
	s_addc_u32 s39, s69, 0
	s_add_i32 s33, s54, s75
	global_load_lds_dwordx4 v199, s[68:69]
	s_mov_b32 m0, s33
	s_nop 0
	global_load_lds_dwordx4 v96, s[38:39]
	s_add_i32 m0, s33, 0x2000
	s_nop 0
	global_load_lds_dwordx4 v134, s[38:39]
	s_mov_b32 m0, s58
	s_nop 0
	global_load_lds_dwordx4 v227, s[82:83]
	s_mov_b32 m0, s59
	s_nop 0
	global_load_lds_dwordx4 v229, s[82:83]
	s_waitcnt vmcnt(8)
	s_waitcnt lgkmcnt(0)
	s_setprio 1
	s_barrier
	v_mfma_f32_16x16x32_bf16 v[60:63], v[154:157], v[186:189], v[60:63]
	v_mfma_f32_16x16x32_bf16 v[56:59], v[162:165], v[186:189], v[56:59]
	v_mfma_f32_16x16x32_bf16 v[44:47], v[154:157], v[194:197], v[44:47]
	v_mfma_f32_16x16x32_bf16 v[40:43], v[162:165], v[194:197], v[40:43]
	v_mfma_f32_16x16x32_bf16 v[28:31], v[154:157], v[210:213], v[28:31]
	v_mfma_f32_16x16x32_bf16 v[24:27], v[162:165], v[210:213], v[24:27]
	v_mfma_f32_16x16x32_bf16 v[12:15], v[154:157], v[218:221], v[12:15]
	v_mfma_f32_16x16x32_bf16 v[8:11], v[162:165], v[218:221], v[8:11]
	v_mfma_f32_16x16x32_bf16 v[60:63], v[158:161], v[190:193], v[60:63]
	v_mfma_f32_16x16x32_bf16 v[56:59], v[166:169], v[190:193], v[56:59]
	v_mfma_f32_16x16x32_bf16 v[44:47], v[158:161], v[202:205], v[44:47]
	v_mfma_f32_16x16x32_bf16 v[40:43], v[166:169], v[202:205], v[40:43]
	v_mfma_f32_16x16x32_bf16 v[28:31], v[158:161], v[214:217], v[28:31]
	v_mfma_f32_16x16x32_bf16 v[24:27], v[166:169], v[214:217], v[24:27]
	v_mfma_f32_16x16x32_bf16 v[12:15], v[158:161], v[222:225], v[12:15]
	v_mfma_f32_16x16x32_bf16 v[8:11], v[166:169], v[222:225], v[8:11]
	v_mfma_f32_16x16x32_bf16 v[52:55], v[170:173], v[186:189], v[52:55]
	v_mfma_f32_16x16x32_bf16 v[48:51], v[178:181], v[186:189], v[48:51]
	v_mfma_f32_16x16x32_bf16 v[36:39], v[170:173], v[194:197], v[36:39]
	v_mfma_f32_16x16x32_bf16 v[32:35], v[178:181], v[194:197], v[32:35]
	v_mfma_f32_16x16x32_bf16 v[20:23], v[170:173], v[210:213], v[20:23]
	v_mfma_f32_16x16x32_bf16 v[16:19], v[178:181], v[210:213], v[16:19]
	v_mfma_f32_16x16x32_bf16 v[4:7], v[170:173], v[218:221], v[4:7]
	v_mfma_f32_16x16x32_bf16 v[0:3], v[178:181], v[218:221], v[0:3]
	v_mfma_f32_16x16x32_bf16 v[52:55], v[174:177], v[190:193], v[52:55]
	v_mfma_f32_16x16x32_bf16 v[48:51], v[182:185], v[190:193], v[48:51]
	v_mfma_f32_16x16x32_bf16 v[36:39], v[174:177], v[202:205], v[36:39]
	v_mfma_f32_16x16x32_bf16 v[32:35], v[182:185], v[202:205], v[32:35]
	v_mfma_f32_16x16x32_bf16 v[20:23], v[174:177], v[214:217], v[20:23]
	v_mfma_f32_16x16x32_bf16 v[16:19], v[182:185], v[214:217], v[16:19]
	v_mfma_f32_16x16x32_bf16 v[4:7], v[174:177], v[222:225], v[4:7]
	v_mfma_f32_16x16x32_bf16 v[0:3], v[182:185], v[222:225], v[0:3]
	s_barrier
	s_setprio 0
	s_add_i32 s28, s28, 2
	s_add_u32 s52, s52, 0x100
	s_addc_u32 s53, s53, 0
	s_add_u32 s20, s20, 0x100
	s_addc_u32 s25, s25, 0
	s_cmp_gt_u32 s28, 29
	s_cbranch_scc0 .LBB0_1284
	v_mov_b32_e32 v243, 1
	v_readlane_b32 s6, v251, 54
	v_readlane_b32 s7, v251, 55
	s_and_b64 vcc, exec, s[6:7]
	s_cbranch_vccz .LBB0_1287
	s_barrier
